# attention hot loop: pipelined QK/PV LDS fragment reads (4 buffers), merged chunk-list reads, early mask reads, cbias in SGPR
# speedup vs baseline: 1.0427x; 1.0223x over previous
.LBB0_155:
.Lc3_entry:
	v_cmp_le_i32_e64 s[70:71], v3, v24
	s_and_saveexec_b64 s[2:3], s[70:71]
	s_cbranch_execz .LBB0_158
	s_mov_b64 s[70:71], 0

.Lc3_steps:
	v_pk_mul_f32 v[8:9], v[6:7], v[160:161]
	v_pk_fma_f32 v[8:9], v[4:5], v[158:159], v[8:9]
	v_add_f32_e32 v20, v8, v9
	v_pk_mul_f32 v[12:13], v[154:155], v[170:171] op_sel_hi:[1,0]
	v_pk_mul_f32 v[14:15], v[156:157], v[170:171] op_sel_hi:[1,0]
	v_add_f32_dpp v20, v20, v20 quad_perm:[1,0,3,2] row_mask:0xf bank_mask:0xf bound_ctrl:1
	v_pk_fma_f32 v[12:13], v[4:5], v[150:151], v[12:13]
	v_pk_fma_f32 v[14:15], v[6:7], v[152:153], v[14:15]
	v_add_f32_dpp v20, v20, v20 quad_perm:[2,3,0,1] row_mask:0xf bank_mask:0xf bound_ctrl:1
	ds_read_b128 v[210:213], v0 offset:11776
	ds_read_b128 v[214:217], v0 offset:12032
	v_add_f32_dpp v20, v20, v20 row_half_mirror row_mask:0xf bank_mask:0xf bound_ctrl:1
	ds_read_b128 v[218:221], v0 offset:12288
	ds_read_b128 v[222:225], v0 offset:12544
	v_add_f32_dpp v20, v20, v20 row_mirror row_mask:0xf bank_mask:0xf bound_ctrl:1
	ds_read_b128 v[226:229], v0 offset:12800
	ds_read_b32 v230, v18 offset:29728
	v_pk_fma_f32 v[4:5], v[162:163], v[20:21], v[12:13] op_sel_hi:[1,0,1]
	v_pk_fma_f32 v[6:7], v[164:165], v[20:21], v[14:15] op_sel_hi:[1,0,1]
	s_waitcnt lgkmcnt(6)
	v_pk_mul_f32 v[8:9], v[6:7], v[182:183]
	v_pk_fma_f32 v[8:9], v[4:5], v[180:181], v[8:9]
	v_pk_mul_f32 v[10:11], v[6:7], v[168:169]
	v_add_f32_e32 v20, v8, v9
	v_pk_fma_f32 v[10:11], v[4:5], v[166:167], v[10:11]
	v_pk_mul_f32 v[12:13], v[176:177], v[192:193] op_sel_hi:[1,0]
	v_add_f32_dpp v20, v20, v20 quad_perm:[1,0,3,2] row_mask:0xf bank_mask:0xf bound_ctrl:1
	v_add_f32_e32 v30, v10, v11
	v_pk_mul_f32 v[14:15], v[178:179], v[192:193] op_sel_hi:[1,0]
	v_add_f32_dpp v20, v20, v20 quad_perm:[2,3,0,1] row_mask:0xf bank_mask:0xf bound_ctrl:1
	ds_read_b128 v[150:153], v0 offset:13056
	ds_read_b128 v[154:157], v0 offset:13312
	v_add_f32_dpp v20, v20, v20 row_half_mirror row_mask:0xf bank_mask:0xf bound_ctrl:1
	ds_read_b128 v[158:161], v0 offset:13568
	ds_read_b128 v[162:165], v0 offset:13824
	v_add_f32_dpp v20, v20, v20 row_mirror row_mask:0xf bank_mask:0xf bound_ctrl:1
	v_pk_fma_f32 v[12:13], v[4:5], v[172:173], v[12:13]
	v_pk_fma_f32 v[14:15], v[6:7], v[174:175], v[14:15]
	ds_read_b128 v[166:169], v0 offset:14080
	ds_read_b32 v170, v18 offset:29744
	v_pk_fma_f32 v[4:5], v[184:185], v[20:21], v[12:13] op_sel_hi:[1,0,1]
	v_pk_fma_f32 v[6:7], v[186:187], v[20:21], v[14:15] op_sel_hi:[1,0,1]
	s_waitcnt lgkmcnt(6)
	v_pk_mul_f32 v[8:9], v[6:7], v[220:221]
	v_pk_fma_f32 v[8:9], v[4:5], v[218:219], v[8:9]
	v_pk_mul_f32 v[10:11], v[6:7], v[190:191]
	v_add_f32_e32 v20, v8, v9
	v_pk_fma_f32 v[10:11], v[4:5], v[188:189], v[10:11]
	v_pk_mul_f32 v[12:13], v[214:215], v[230:231] op_sel_hi:[1,0]
	v_add_f32_dpp v20, v20, v20 quad_perm:[1,0,3,2] row_mask:0xf bank_mask:0xf bound_ctrl:1
	v_add_f32_e32 v31, v10, v11
	v_pk_mul_f32 v[14:15], v[216:217], v[230:231] op_sel_hi:[1,0]
	v_add_f32_dpp v20, v20, v20 quad_perm:[2,3,0,1] row_mask:0xf bank_mask:0xf bound_ctrl:1
	ds_read_b128 v[172:175], v0 offset:14336
	ds_read_b128 v[176:179], v0 offset:14592
	v_add_f32_dpp v20, v20, v20 row_half_mirror row_mask:0xf bank_mask:0xf bound_ctrl:1
	ds_read_b128 v[180:183], v0 offset:14848
	ds_read_b128 v[184:187], v0 offset:15104
	v_add_f32_dpp v20, v20, v20 row_mirror row_mask:0xf bank_mask:0xf bound_ctrl:1
	v_pk_fma_f32 v[12:13], v[4:5], v[210:211], v[12:13]
	v_pk_fma_f32 v[14:15], v[6:7], v[212:213], v[14:15]
	ds_read_b128 v[188:191], v0 offset:15360
	ds_read_b32 v192, v18 offset:29760
	v_pk_fma_f32 v[4:5], v[222:223], v[20:21], v[12:13] op_sel_hi:[1,0,1]
	v_pk_fma_f32 v[6:7], v[224:225], v[20:21], v[14:15] op_sel_hi:[1,0,1]
	s_waitcnt lgkmcnt(6)
	v_pk_mul_f32 v[8:9], v[6:7], v[160:161]
	v_pk_fma_f32 v[8:9], v[4:5], v[158:159], v[8:9]
	v_pk_mul_f32 v[10:11], v[6:7], v[228:229]
	v_add_f32_e32 v20, v8, v9
	v_pk_fma_f32 v[10:11], v[4:5], v[226:227], v[10:11]
	v_pk_mul_f32 v[12:13], v[154:155], v[170:171] op_sel_hi:[1,0]
	v_add_f32_dpp v20, v20, v20 quad_perm:[1,0,3,2] row_mask:0xf bank_mask:0xf bound_ctrl:1
	v_add_f32_e32 v32, v10, v11
	v_pk_mul_f32 v[14:15], v[156:157], v[170:171] op_sel_hi:[1,0]
	v_add_f32_dpp v20, v20, v20 quad_perm:[2,3,0,1] row_mask:0xf bank_mask:0xf bound_ctrl:1
	ds_read_b128 v[210:213], v0 offset:15616
	ds_read_b128 v[214:217], v0 offset:15872
	v_add_f32_dpp v20, v20, v20 row_half_mirror row_mask:0xf bank_mask:0xf bound_ctrl:1
	ds_read_b128 v[218:221], v0 offset:16128
	ds_read_b128 v[222:225], v0 offset:16384
	v_add_f32_dpp v20, v20, v20 row_mirror row_mask:0xf bank_mask:0xf bound_ctrl:1
	v_pk_fma_f32 v[12:13], v[4:5], v[150:151], v[12:13]
	v_pk_fma_f32 v[14:15], v[6:7], v[152:153], v[14:15]
	ds_read_b128 v[226:229], v0 offset:16640
	ds_read_b32 v230, v18 offset:29776
	v_pk_fma_f32 v[4:5], v[162:163], v[20:21], v[12:13] op_sel_hi:[1,0,1]
	v_pk_fma_f32 v[6:7], v[164:165], v[20:21], v[14:15] op_sel_hi:[1,0,1]
	s_waitcnt lgkmcnt(6)
	v_pk_mul_f32 v[8:9], v[6:7], v[182:183]
	v_pk_fma_f32 v[8:9], v[4:5], v[180:181], v[8:9]
	v_pk_mul_f32 v[10:11], v[6:7], v[168:169]
	v_add_f32_e32 v20, v8, v9
	v_pk_fma_f32 v[10:11], v[4:5], v[166:167], v[10:11]
	v_pk_mul_f32 v[12:13], v[176:177], v[192:193] op_sel_hi:[1,0]
	v_add_f32_dpp v20, v20, v20 quad_perm:[1,0,3,2] row_mask:0xf bank_mask:0xf bound_ctrl:1
	v_add_f32_e32 v33, v10, v11
	v_pk_mul_f32 v[14:15], v[178:179], v[192:193] op_sel_hi:[1,0]
	v_add_f32_dpp v20, v20, v20 quad_perm:[2,3,0,1] row_mask:0xf bank_mask:0xf bound_ctrl:1
	ds_read_b128 v[150:153], v0 offset:16896
	ds_read_b128 v[154:157], v0 offset:17152
	v_add_f32_dpp v20, v20, v20 row_half_mirror row_mask:0xf bank_mask:0xf bound_ctrl:1
	ds_read_b128 v[158:161], v0 offset:17408
	ds_read_b128 v[162:165], v0 offset:17664
	v_add_f32_dpp v20, v20, v20 row_mirror row_mask:0xf bank_mask:0xf bound_ctrl:1
	v_pk_fma_f32 v[12:13], v[4:5], v[172:173], v[12:13]
	v_pk_fma_f32 v[14:15], v[6:7], v[174:175], v[14:15]
	ds_read_b128 v[166:169], v0 offset:17920
	ds_read_b32 v170, v18 offset:29792
	v_pk_fma_f32 v[4:5], v[184:185], v[20:21], v[12:13] op_sel_hi:[1,0,1]
	v_pk_fma_f32 v[6:7], v[186:187], v[20:21], v[14:15] op_sel_hi:[1,0,1]
	s_waitcnt lgkmcnt(6)
	v_pk_mul_f32 v[8:9], v[6:7], v[220:221]
	v_pk_fma_f32 v[8:9], v[4:5], v[218:219], v[8:9]
	v_pk_mul_f32 v[10:11], v[6:7], v[190:191]
	v_add_f32_e32 v20, v8, v9
	v_pk_fma_f32 v[10:11], v[4:5], v[188:189], v[10:11]
	v_pk_mul_f32 v[12:13], v[214:215], v[230:231] op_sel_hi:[1,0]
	v_add_f32_dpp v20, v20, v20 quad_perm:[1,0,3,2] row_mask:0xf bank_mask:0xf bound_ctrl:1
	v_add_f32_e32 v34, v10, v11
	v_pk_mul_f32 v[14:15], v[216:217], v[230:231] op_sel_hi:[1,0]
	v_add_f32_dpp v20, v20, v20 quad_perm:[2,3,0,1] row_mask:0xf bank_mask:0xf bound_ctrl:1
	ds_read_b128 v[172:175], v0 offset:18176
	ds_read_b128 v[176:179], v0 offset:18432
	v_add_f32_dpp v20, v20, v20 row_half_mirror row_mask:0xf bank_mask:0xf bound_ctrl:1
	ds_read_b128 v[180:183], v0 offset:18688
	ds_read_b128 v[184:187], v0 offset:18944
	v_add_f32_dpp v20, v20, v20 row_mirror row_mask:0xf bank_mask:0xf bound_ctrl:1
	v_pk_fma_f32 v[12:13], v[4:5], v[210:211], v[12:13]
	v_pk_fma_f32 v[14:15], v[6:7], v[212:213], v[14:15]
	ds_read_b128 v[188:191], v0 offset:19200
	ds_read_b32 v192, v18 offset:29808
	v_pk_fma_f32 v[4:5], v[222:223], v[20:21], v[12:13] op_sel_hi:[1,0,1]
	v_pk_fma_f32 v[6:7], v[224:225], v[20:21], v[14:15] op_sel_hi:[1,0,1]
	s_waitcnt lgkmcnt(6)
	v_pk_mul_f32 v[8:9], v[6:7], v[160:161]
	v_pk_fma_f32 v[8:9], v[4:5], v[158:159], v[8:9]
	v_pk_mul_f32 v[10:11], v[6:7], v[228:229]
	v_add_f32_e32 v20, v8, v9
	v_pk_fma_f32 v[10:11], v[4:5], v[226:227], v[10:11]
	v_pk_mul_f32 v[12:13], v[154:155], v[170:171] op_sel_hi:[1,0]
	v_add_f32_dpp v20, v20, v20 quad_perm:[1,0,3,2] row_mask:0xf bank_mask:0xf bound_ctrl:1
	v_add_f32_e32 v35, v10, v11
	v_pk_mul_f32 v[14:15], v[156:157], v[170:171] op_sel_hi:[1,0]
	v_add_f32_dpp v20, v20, v20 quad_perm:[2,3,0,1] row_mask:0xf bank_mask:0xf bound_ctrl:1
	ds_read_b128 v[210:213], v0 offset:19456
	ds_read_b128 v[214:217], v0 offset:19712
	v_add_f32_dpp v20, v20, v20 row_half_mirror row_mask:0xf bank_mask:0xf bound_ctrl:1
	ds_read_b128 v[218:221], v0 offset:19968
	ds_read_b128 v[222:225], v0 offset:20224
	v_add_f32_dpp v20, v20, v20 row_mirror row_mask:0xf bank_mask:0xf bound_ctrl:1
	v_pk_fma_f32 v[12:13], v[4:5], v[150:151], v[12:13]
	v_pk_fma_f32 v[14:15], v[6:7], v[152:153], v[14:15]
	ds_read_b128 v[226:229], v0 offset:20480
	ds_read_b32 v230, v18 offset:29824
	v_pk_fma_f32 v[4:5], v[162:163], v[20:21], v[12:13] op_sel_hi:[1,0,1]
	v_pk_fma_f32 v[6:7], v[164:165], v[20:21], v[14:15] op_sel_hi:[1,0,1]
	s_waitcnt lgkmcnt(6)
	v_pk_mul_f32 v[8:9], v[6:7], v[182:183]
	v_pk_fma_f32 v[8:9], v[4:5], v[180:181], v[8:9]
	v_pk_mul_f32 v[10:11], v[6:7], v[168:169]
	v_add_f32_e32 v20, v8, v9
	v_pk_fma_f32 v[10:11], v[4:5], v[166:167], v[10:11]
	v_pk_mul_f32 v[12:13], v[176:177], v[192:193] op_sel_hi:[1,0]
	v_add_f32_dpp v20, v20, v20 quad_perm:[1,0,3,2] row_mask:0xf bank_mask:0xf bound_ctrl:1
	v_add_f32_e32 v36, v10, v11
	v_pk_mul_f32 v[14:15], v[178:179], v[192:193] op_sel_hi:[1,0]
	v_add_f32_dpp v20, v20, v20 quad_perm:[2,3,0,1] row_mask:0xf bank_mask:0xf bound_ctrl:1
	ds_read_b128 v[150:153], v0 offset:20736
	ds_read_b128 v[154:157], v0 offset:20992
	v_add_f32_dpp v20, v20, v20 row_half_mirror row_mask:0xf bank_mask:0xf bound_ctrl:1
	ds_read_b128 v[158:161], v0 offset:21248
	ds_read_b128 v[162:165], v0 offset:21504
	v_add_f32_dpp v20, v20, v20 row_mirror row_mask:0xf bank_mask:0xf bound_ctrl:1
	v_pk_fma_f32 v[12:13], v[4:5], v[172:173], v[12:13]
	v_pk_fma_f32 v[14:15], v[6:7], v[174:175], v[14:15]
	ds_read_b128 v[166:169], v0 offset:21760
	ds_read_b32 v170, v18 offset:29840
	v_pk_fma_f32 v[4:5], v[184:185], v[20:21], v[12:13] op_sel_hi:[1,0,1]
	v_pk_fma_f32 v[6:7], v[186:187], v[20:21], v[14:15] op_sel_hi:[1,0,1]
	s_waitcnt lgkmcnt(6)
	v_pk_mul_f32 v[8:9], v[6:7], v[220:221]
	v_pk_fma_f32 v[8:9], v[4:5], v[218:219], v[8:9]
	v_pk_mul_f32 v[10:11], v[6:7], v[190:191]
	v_add_f32_e32 v20, v8, v9
	v_pk_fma_f32 v[10:11], v[4:5], v[188:189], v[10:11]
	v_pk_mul_f32 v[12:13], v[214:215], v[230:231] op_sel_hi:[1,0]
	v_add_f32_dpp v20, v20, v20 quad_perm:[1,0,3,2] row_mask:0xf bank_mask:0xf bound_ctrl:1
	v_add_f32_e32 v37, v10, v11
	v_pk_mul_f32 v[14:15], v[216:217], v[230:231] op_sel_hi:[1,0]
	v_add_f32_dpp v20, v20, v20 quad_perm:[2,3,0,1] row_mask:0xf bank_mask:0xf bound_ctrl:1
	ds_read_b128 v[172:175], v0 offset:22016
	ds_read_b128 v[176:179], v0 offset:22272
	v_add_f32_dpp v20, v20, v20 row_half_mirror row_mask:0xf bank_mask:0xf bound_ctrl:1
	ds_read_b128 v[180:183], v0 offset:22528
	ds_read_b128 v[184:187], v0 offset:22784
	v_add_f32_dpp v20, v20, v20 row_mirror row_mask:0xf bank_mask:0xf bound_ctrl:1
	v_pk_fma_f32 v[12:13], v[4:5], v[210:211], v[12:13]
	v_pk_fma_f32 v[14:15], v[6:7], v[212:213], v[14:15]
	ds_read_b128 v[188:191], v0 offset:23040
	ds_read_b32 v192, v18 offset:29856
	v_pk_fma_f32 v[4:5], v[222:223], v[20:21], v[12:13] op_sel_hi:[1,0,1]
	v_pk_fma_f32 v[6:7], v[224:225], v[20:21], v[14:15] op_sel_hi:[1,0,1]
	s_waitcnt lgkmcnt(6)
	v_pk_mul_f32 v[8:9], v[6:7], v[160:161]
	v_pk_fma_f32 v[8:9], v[4:5], v[158:159], v[8:9]
	v_pk_mul_f32 v[10:11], v[6:7], v[228:229]
	v_add_f32_e32 v20, v8, v9
	v_pk_fma_f32 v[10:11], v[4:5], v[226:227], v[10:11]
	v_pk_mul_f32 v[12:13], v[154:155], v[170:171] op_sel_hi:[1,0]
	v_add_f32_dpp v20, v20, v20 quad_perm:[1,0,3,2] row_mask:0xf bank_mask:0xf bound_ctrl:1
	v_add_f32_e32 v38, v10, v11
	v_pk_mul_f32 v[14:15], v[156:157], v[170:171] op_sel_hi:[1,0]
	v_add_f32_dpp v20, v20, v20 quad_perm:[2,3,0,1] row_mask:0xf bank_mask:0xf bound_ctrl:1
	ds_read_b128 v[210:213], v0 offset:23296
	ds_read_b128 v[214:217], v0 offset:23552
	v_add_f32_dpp v20, v20, v20 row_half_mirror row_mask:0xf bank_mask:0xf bound_ctrl:1
	ds_read_b128 v[218:221], v0 offset:23808
	ds_read_b128 v[222:225], v0 offset:24064
	v_add_f32_dpp v20, v20, v20 row_mirror row_mask:0xf bank_mask:0xf bound_ctrl:1
	v_pk_fma_f32 v[12:13], v[4:5], v[150:151], v[12:13]
	v_pk_fma_f32 v[14:15], v[6:7], v[152:153], v[14:15]
	ds_read_b128 v[226:229], v0 offset:24320
	ds_read_b32 v230, v18 offset:29872
	v_pk_fma_f32 v[4:5], v[162:163], v[20:21], v[12:13] op_sel_hi:[1,0,1]
	v_pk_fma_f32 v[6:7], v[164:165], v[20:21], v[14:15] op_sel_hi:[1,0,1]
	s_waitcnt lgkmcnt(6)
	v_pk_mul_f32 v[8:9], v[6:7], v[182:183]
	v_pk_fma_f32 v[8:9], v[4:5], v[180:181], v[8:9]
	v_pk_mul_f32 v[10:11], v[6:7], v[168:169]
	v_add_f32_e32 v20, v8, v9
	v_pk_fma_f32 v[10:11], v[4:5], v[166:167], v[10:11]
	v_pk_mul_f32 v[12:13], v[176:177], v[192:193] op_sel_hi:[1,0]
	v_add_f32_dpp v20, v20, v20 quad_perm:[1,0,3,2] row_mask:0xf bank_mask:0xf bound_ctrl:1
	v_add_f32_e32 v39, v10, v11
	v_pk_mul_f32 v[14:15], v[178:179], v[192:193] op_sel_hi:[1,0]
	v_add_f32_dpp v20, v20, v20 quad_perm:[2,3,0,1] row_mask:0xf bank_mask:0xf bound_ctrl:1
	ds_read_b128 v[150:153], v0 offset:24576
	ds_read_b128 v[154:157], v0 offset:24832
	v_add_f32_dpp v20, v20, v20 row_half_mirror row_mask:0xf bank_mask:0xf bound_ctrl:1
	ds_read_b128 v[158:161], v0 offset:25088
	ds_read_b128 v[162:165], v0 offset:25344
	v_add_f32_dpp v20, v20, v20 row_mirror row_mask:0xf bank_mask:0xf bound_ctrl:1
	v_pk_fma_f32 v[12:13], v[4:5], v[172:173], v[12:13]
	v_pk_fma_f32 v[14:15], v[6:7], v[174:175], v[14:15]
	ds_read_b128 v[166:169], v0 offset:25600
	ds_read_b32 v170, v18 offset:29888
	v_pk_fma_f32 v[4:5], v[184:185], v[20:21], v[12:13] op_sel_hi:[1,0,1]
	v_pk_fma_f32 v[6:7], v[186:187], v[20:21], v[14:15] op_sel_hi:[1,0,1]
	s_waitcnt lgkmcnt(6)
	v_pk_mul_f32 v[8:9], v[6:7], v[220:221]
	v_pk_fma_f32 v[8:9], v[4:5], v[218:219], v[8:9]
	v_pk_mul_f32 v[10:11], v[6:7], v[190:191]
	v_add_f32_e32 v20, v8, v9
	v_pk_fma_f32 v[10:11], v[4:5], v[188:189], v[10:11]
	v_pk_mul_f32 v[12:13], v[214:215], v[230:231] op_sel_hi:[1,0]
	v_add_f32_dpp v20, v20, v20 quad_perm:[1,0,3,2] row_mask:0xf bank_mask:0xf bound_ctrl:1
	v_add_f32_e32 v40, v10, v11
	v_pk_mul_f32 v[14:15], v[216:217], v[230:231] op_sel_hi:[1,0]
	v_add_f32_dpp v20, v20, v20 quad_perm:[2,3,0,1] row_mask:0xf bank_mask:0xf bound_ctrl:1
	ds_read_b128 v[172:175], v0 offset:25856
	ds_read_b128 v[176:179], v0 offset:26112
	v_add_f32_dpp v20, v20, v20 row_half_mirror row_mask:0xf bank_mask:0xf bound_ctrl:1
	ds_read_b128 v[180:183], v0 offset:26368
	ds_read_b128 v[184:187], v0 offset:26624
	v_add_f32_dpp v20, v20, v20 row_mirror row_mask:0xf bank_mask:0xf bound_ctrl:1
	v_pk_fma_f32 v[12:13], v[4:5], v[210:211], v[12:13]
	v_pk_fma_f32 v[14:15], v[6:7], v[212:213], v[14:15]
	ds_read_b128 v[188:191], v0 offset:26880
	ds_read_b32 v192, v18 offset:29904
	v_pk_fma_f32 v[4:5], v[222:223], v[20:21], v[12:13] op_sel_hi:[1,0,1]
	v_pk_fma_f32 v[6:7], v[224:225], v[20:21], v[14:15] op_sel_hi:[1,0,1]
	s_waitcnt lgkmcnt(6)
	v_pk_mul_f32 v[8:9], v[6:7], v[160:161]
	v_pk_fma_f32 v[8:9], v[4:5], v[158:159], v[8:9]
	v_pk_mul_f32 v[10:11], v[6:7], v[228:229]
	v_add_f32_e32 v20, v8, v9
	v_pk_fma_f32 v[10:11], v[4:5], v[226:227], v[10:11]
	v_pk_mul_f32 v[12:13], v[154:155], v[170:171] op_sel_hi:[1,0]
	v_add_f32_dpp v20, v20, v20 quad_perm:[1,0,3,2] row_mask:0xf bank_mask:0xf bound_ctrl:1
	v_add_f32_e32 v41, v10, v11
	v_pk_mul_f32 v[14:15], v[156:157], v[170:171] op_sel_hi:[1,0]
	v_add_f32_dpp v20, v20, v20 quad_perm:[2,3,0,1] row_mask:0xf bank_mask:0xf bound_ctrl:1
	ds_read_b128 v[210:213], v0 offset:27136
	ds_read_b128 v[214:217], v0 offset:27392
	v_add_f32_dpp v20, v20, v20 row_half_mirror row_mask:0xf bank_mask:0xf bound_ctrl:1
	ds_read_b128 v[218:221], v0 offset:27648
	ds_read_b128 v[222:225], v0 offset:27904
	v_add_f32_dpp v20, v20, v20 row_mirror row_mask:0xf bank_mask:0xf bound_ctrl:1
	v_pk_fma_f32 v[12:13], v[4:5], v[150:151], v[12:13]
	v_pk_fma_f32 v[14:15], v[6:7], v[152:153], v[14:15]
	ds_read_b128 v[226:229], v0 offset:28160
	ds_read_b32 v230, v18 offset:29920
	v_pk_fma_f32 v[4:5], v[162:163], v[20:21], v[12:13] op_sel_hi:[1,0,1]
	v_pk_fma_f32 v[6:7], v[164:165], v[20:21], v[14:15] op_sel_hi:[1,0,1]
	s_waitcnt lgkmcnt(6)
	v_pk_mul_f32 v[8:9], v[6:7], v[182:183]
	v_pk_fma_f32 v[8:9], v[4:5], v[180:181], v[8:9]
	v_pk_mul_f32 v[10:11], v[6:7], v[168:169]
	v_add_f32_e32 v20, v8, v9
	v_pk_fma_f32 v[10:11], v[4:5], v[166:167], v[10:11]
	v_pk_mul_f32 v[12:13], v[176:177], v[192:193] op_sel_hi:[1,0]
	v_add_f32_dpp v20, v20, v20 quad_perm:[1,0,3,2] row_mask:0xf bank_mask:0xf bound_ctrl:1
	v_add_f32_e32 v42, v10, v11
	v_pk_mul_f32 v[14:15], v[178:179], v[192:193] op_sel_hi:[1,0]
	v_add_f32_dpp v20, v20, v20 quad_perm:[2,3,0,1] row_mask:0xf bank_mask:0xf bound_ctrl:1
	ds_read_b128 v[150:153], v0 offset:28416
	ds_read_b128 v[154:157], v0 offset:28672
	v_add_f32_dpp v20, v20, v20 row_half_mirror row_mask:0xf bank_mask:0xf bound_ctrl:1
	ds_read_b128 v[158:161], v0 offset:28928
	ds_read_b128 v[162:165], v0 offset:29184
	v_add_f32_dpp v20, v20, v20 row_mirror row_mask:0xf bank_mask:0xf bound_ctrl:1
	v_pk_fma_f32 v[12:13], v[4:5], v[172:173], v[12:13]
	v_pk_fma_f32 v[14:15], v[6:7], v[174:175], v[14:15]
	ds_read_b128 v[166:169], v0 offset:29440
	ds_read_b32 v170, v18 offset:29936
	v_pk_fma_f32 v[4:5], v[184:185], v[20:21], v[12:13] op_sel_hi:[1,0,1]
	v_pk_fma_f32 v[6:7], v[186:187], v[20:21], v[14:15] op_sel_hi:[1,0,1]
	ds_read_b32 v3, v22
	s_waitcnt lgkmcnt(7)
	v_pk_mul_f32 v[8:9], v[6:7], v[220:221]
	v_pk_fma_f32 v[8:9], v[4:5], v[218:219], v[8:9]
	v_pk_mul_f32 v[10:11], v[6:7], v[190:191]
	v_add_f32_e32 v20, v8, v9
	v_pk_fma_f32 v[10:11], v[4:5], v[188:189], v[10:11]
	v_pk_mul_f32 v[12:13], v[214:215], v[230:231] op_sel_hi:[1,0]
	v_add_f32_dpp v20, v20, v20 quad_perm:[1,0,3,2] row_mask:0xf bank_mask:0xf bound_ctrl:1
	v_add_f32_e32 v43, v10, v11
	v_pk_mul_f32 v[14:15], v[216:217], v[230:231] op_sel_hi:[1,0]
	v_add_f32_dpp v20, v20, v20 quad_perm:[2,3,0,1] row_mask:0xf bank_mask:0xf bound_ctrl:1
	v_pk_fma_f32 v[12:13], v[4:5], v[210:211], v[12:13]
	v_pk_fma_f32 v[14:15], v[6:7], v[212:213], v[14:15]
	v_add_f32_dpp v20, v20, v20 row_half_mirror row_mask:0xf bank_mask:0xf bound_ctrl:1
	s_nop 1
	v_add_f32_dpp v20, v20, v20 row_mirror row_mask:0xf bank_mask:0xf bound_ctrl:1
	v_pk_fma_f32 v[4:5], v[222:223], v[20:21], v[12:13] op_sel_hi:[1,0,1]
	v_pk_fma_f32 v[6:7], v[224:225], v[20:21], v[14:15] op_sel_hi:[1,0,1]
	s_waitcnt lgkmcnt(0)
	v_pk_mul_f32 v[8:9], v[6:7], v[160:161]
	v_pk_fma_f32 v[8:9], v[4:5], v[158:159], v[8:9]
	v_pk_mul_f32 v[10:11], v[6:7], v[228:229]
	v_add_f32_e32 v20, v8, v9
	v_pk_fma_f32 v[10:11], v[4:5], v[226:227], v[10:11]
	v_pk_mul_f32 v[12:13], v[154:155], v[170:171] op_sel_hi:[1,0]
	v_add_f32_dpp v20, v20, v20 quad_perm:[1,0,3,2] row_mask:0xf bank_mask:0xf bound_ctrl:1
	v_add_f32_e32 v44, v10, v11
	v_pk_mul_f32 v[14:15], v[156:157], v[170:171] op_sel_hi:[1,0]
	v_add_f32_dpp v20, v20, v20 quad_perm:[2,3,0,1] row_mask:0xf bank_mask:0xf bound_ctrl:1
	v_pk_fma_f32 v[12:13], v[4:5], v[150:151], v[12:13]
	v_pk_fma_f32 v[14:15], v[6:7], v[152:153], v[14:15]
	v_add_f32_dpp v20, v20, v20 row_half_mirror row_mask:0xf bank_mask:0xf bound_ctrl:1
	s_nop 1
	v_add_f32_dpp v20, v20, v20 row_mirror row_mask:0xf bank_mask:0xf bound_ctrl:1
	v_pk_fma_f32 v[4:5], v[162:163], v[20:21], v[12:13] op_sel_hi:[1,0,1]
	v_pk_fma_f32 v[6:7], v[164:165], v[20:21], v[14:15] op_sel_hi:[1,0,1]
	v_pk_mul_f32 v[10:11], v[6:7], v[168:169]
	v_pk_fma_f32 v[10:11], v[4:5], v[166:167], v[10:11]
	v_add_u32_e32 v2, v1, v232
	v_add_f32_e32 v45, v10, v11
	s_add_i32 s72, s72, 1
	s_cmpk_eq_i32 s72, 0x200
	s_cbranch_scc1 .Lc3_last
	v_cmp_gt_i32_e32 vcc, v3, v23
	s_cbranch_vccz .Lc3_slow
	s_mul_i32 s0, s73, 0x5100
	v_add_u32_e32 v1, s0, v87
	v_lshl_add_u32 v0, v125, 2, v1
	v_lshl_add_u32 v18, v78, 2, v1
	ds_read_b128 v[150:153], v0 offset:9216
	ds_read_b128 v[154:157], v0 offset:9472
	ds_read_b128 v[158:161], v0 offset:9728
	ds_read_b128 v[162:165], v0 offset:9984
	ds_read_b128 v[166:169], v0 offset:10240
	ds_read_b32 v170, v18 offset:29696
	ds_read_b128 v[172:175], v0 offset:10496
	ds_read_b128 v[176:179], v0 offset:10752
	ds_read_b128 v[180:183], v0 offset:11008
	ds_read_b128 v[184:187], v0 offset:11264
	ds_read_b128 v[188:191], v0 offset:11520
	ds_read_b32 v192, v18 offset:29712
	s_add_i32 s73, s73, 1
	s_cmp_eq_u32 s73, 3
	s_cselect_b32 s73, 0, s73
	s_addc_u32 s1, s1, 0
	ds_write_b128 v2, v[30:33] offset:9216
	ds_write_b128 v2, v[34:37] offset:10336
	ds_write_b128 v2, v[38:41] offset:11456
	ds_write_b128 v2, v[42:45] offset:12576
	v_add_u32_e32 v24, 1, v24
	ds_write_b32 v19, v24 offset:16
	v_mov_b32_e32 v19, v22
	v_mov_b32_e32 v24, v23
	v_lshl_add_u32 v22, s73, 2, v123
	v_add_u32_e32 v23, s1, v130
	s_waitcnt lgkmcnt(11)
	s_branch .Lc3_steps
.Lc3_slow:
	ds_write_b128 v2, v[30:33] offset:9216
	ds_write_b128 v2, v[34:37] offset:10336
	ds_write_b128 v2, v[38:41] offset:11456
	ds_write_b128 v2, v[42:45] offset:12576
	v_add_u32_e32 v24, 1, v24
	ds_write_b32 v19, v24 offset:16
	v_mov_b32_e32 v19, v22
	v_mov_b32_e32 v24, v23
	s_branch .Lc3_entry
.Lc3_last:
	ds_write_b128 v2, v[30:33] offset:9216
	ds_write_b128 v2, v[34:37] offset:10336
	ds_write_b128 v2, v[38:41] offset:11456
	ds_write_b128 v2, v[42:45] offset:12576
	v_add_u32_e32 v24, 1, v24
	ds_write_b32 v19, v24 offset:16
	v_mov_b32_e32 v19, v22
	v_mov_b32_e32 v24, v23

.LBB0_619:
	s_or_b64 exec, exec, s[0:1]
	v_lshlrev_b32_e32 v29, 5, v111
	v_add_u32_e32 v0, s68, v29
	v_or_b32_e32 v160, v0, v109
	v_or_b32_e32 v156, 16, v160
	v_ashrrev_i32_e32 v161, 31, v160
	v_ashrrev_i32_e32 v157, 31, v156
	v_lshlrev_b64 v[164:165], 12, v[160:161]
	v_lshlrev_b64 v[162:163], 12, v[156:157]
	v_lshl_add_u64 v[12:13], v[82:83], 0, v[164:165]
	v_lshl_add_u64 v[30:31], v[82:83], 0, v[162:163]
	s_waitcnt lgkmcnt(0)
	s_barrier
	flat_load_dwordx4 v[0:3], v[12:13]
	flat_load_dwordx4 v[4:7], v[12:13] offset:64
	flat_load_dwordx4 v[8:11], v[12:13] offset:128
	s_nop 0
	flat_load_dwordx4 v[12:15], v[12:13] offset:192
	s_nop 0
	flat_load_dwordx4 v[16:19], v[30:31]
	flat_load_dwordx4 v[20:23], v[30:31] offset:64
	flat_load_dwordx4 v[24:27], v[30:31] offset:128
	flat_load_dwordx4 v[32:35], v[30:31] offset:192
	v_readlane_b32 s0, v246, 6
	s_lshl_b32 s26, s69, 7
	s_lshl_b32 s27, s69, 20
	v_mov_b32_e32 v30, s0
	ds_read_b32 v30, v30
	s_waitcnt lgkmcnt(0)
	v_cmp_eq_u32_e32 vcc, 0, v30
	v_readfirstlane_b32 s28, v30
	s_cbranch_vccnz .LBB0_679
	v_mov_b32_e32 v52, v154
	v_mov_b32_e32 v30, v155
	v_mov_b32_e32 v31, s50
	ds_read_b32 v31, v31
	s_lshl_b32 s0, s26, 1
	s_add_u32 s12, s43, s0
	s_addc_u32 s13, s42, 0
	s_lshl_b32 s0, s27, 1
	s_add_u32 s14, s45, s0
	s_mov_b32 s0, 0x60000
	s_waitcnt lgkmcnt(0)
	v_mul_hi_i32 v37, v31, s0
	v_mul_lo_u32 v36, v31, s0
	v_lshl_add_u64 v[40:41], s[12:13], 0, v[36:37]
	v_lshlrev_b32_e32 v36, 6, v31
	v_ashrrev_i32_e32 v37, 31, v36
	s_addc_u32 s15, s44, 0
	v_lshlrev_b64 v[36:37], 1, v[36:37]
	v_lshlrev_b32_e32 v31, 3, v52
	v_lshrrev_b32_e32 v53, 4, v52
	s_movk_i32 s0, 0xc00
	v_lshl_add_u64 v[48:49], s[14:15], 0, v[36:37]
	v_and_b32_e32 v42, 0x78, v31
	v_mul_lo_u32 v36, v53, s0
	v_or_b32_e32 v166, v36, v42
	v_mov_b32_e32 v167, v28
	v_lshl_add_u64 v[36:37], v[166:167], 1, v[40:41]
	v_add_u32_e32 v54, 0x200, v52
	global_load_dwordx4 v[36:39], v[36:37], off offset:2048
	v_lshrrev_b32_e32 v55, 4, v54
	v_mul_lo_u32 v43, v55, s0
	v_and_b32_e32 v31, 56, v31
	v_lshlrev_b32_e32 v44, 10, v52
	s_movk_i32 s0, 0xe000
	v_lshlrev_b32_e32 v50, 10, v54
	v_or_b32_e32 v168, v43, v42
	v_mov_b32_e32 v169, v28
	v_and_or_b32 v170, v44, s0, v31
	v_mov_b32_e32 v171, v28
	v_and_or_b32 v172, v50, s0, v31
	v_mov_b32_e32 v173, v28
	v_lshl_add_u64 v[40:41], v[168:169], 1, v[40:41]
	v_lshl_add_u64 v[44:45], v[170:171], 1, v[48:49]
	v_lshl_add_u64 v[48:49], v[172:173], 1, v[48:49]
	global_load_dwordx4 v[40:43], v[40:41], off offset:2048
	v_lshlrev_b32_e32 v56, 4, v52
	global_load_dwordx4 v[44:47], v[44:45], off
	v_and_b32_e32 v31, 0xf0, v56
	global_load_dwordx4 v[48:51], v[48:49], off
	v_add_u32_e32 v57, s54, v31
	v_mul_lo_u32 v157, v53, s83
	v_add_u32_e32 v161, v57, v157
	v_mul_lo_u32 v189, v55, s83
	v_add_u32_e32 v190, v57, v189
	v_readfirstlane_b32 s0, v160
	s_cmp_lt_i32 s28, 1
	s_waitcnt vmcnt(0)
	ds_write_b128 v161, v[36:39]
	v_lshrrev_b32_e32 v38, 3, v52
	v_and_b32_e32 v36, 0x70, v56
	v_mul_lo_u32 v191, v38, s88
	v_lshrrev_b32_e32 v38, 3, v54
	v_add_u32_e32 v37, s79, v36
	v_mul_lo_u32 v193, v38, s88
	v_add_u32_e32 v192, v37, v191
	v_add_u32_e32 v194, v37, v193
	ds_write_b128 v190, v[40:43]
	ds_write_b128 v192, v[44:47]
	ds_write_b128 v194, v[48:51]
	s_waitcnt lgkmcnt(0)
	s_barrier
	s_cbranch_scc1 .LBB0_680
	v_or_b32_e32 v29, v29, v109
	s_add_i32 s1, 0, 0x14440
	v_lshl_add_u32 v195, v29, 4, s1
	v_and_b32_e32 v29, 15, v30
	v_and_b32_e32 v37, -16, v30
	v_ashrrev_i32_e32 v30, 4, v30
	v_lshlrev_b32_e32 v209, 2, v30
	v_lshlrev_b32_e32 v30, 3, v30
	v_add_u32_e32 v38, s54, v37
	v_mul_u32_u24_e32 v39, 0x110, v29
	v_add_u32_e32 v40, s79, v30
	v_mul_u32_u24_e32 v41, 0x90, v29
	v_add_u32_e32 v210, 0, v36
	v_add_u32_e32 v211, 0, v31
	v_add_u32_e32 v36, 0, v37
	v_add_u32_e32 v37, 0, v30
	v_mov_b32_e32 v30, v28
	v_mov_b32_e32 v31, v28
	v_mov_b32_e32 v29, v28
	v_add_u32_e32 v212, v38, v39
	v_add_u32_e32 v213, v40, v41
	v_add_u32_e32 v214, v36, v39
	v_add_u32_e32 v215, v37, v41
	v_mov_b64_e32 v[38:39], v[30:31]
	v_mov_b64_e32 v[42:43], v[30:31]
	v_mov_b64_e32 v[46:47], v[30:31]
	v_mov_b64_e32 v[50:51], v[30:31]
	v_mov_b64_e32 v[54:55], v[30:31]
	v_mov_b64_e32 v[58:59], v[30:31]
	v_mov_b64_e32 v[62:63], v[30:31]
	v_mov_b64_e32 v[66:67], v[30:31]
	v_mov_b64_e32 v[70:71], v[30:31]
	v_mov_b64_e32 v[74:75], v[30:31]
	v_mov_b64_e32 v[78:79], v[30:31]
	v_mov_b64_e32 v[82:83], v[30:31]
	v_mov_b64_e32 v[86:87], v[30:31]
	v_mov_b64_e32 v[90:91], v[30:31]
	v_mov_b64_e32 v[94:95], v[30:31]
	v_mov_b64_e32 v[98:99], v[30:31]
	s_sub_i32 s29, s0, 63
	s_mov_b32 s31, 0
	v_mov_b32_e32 v217, 0xf149f2ca
	v_mov_b32_e32 v117, 0
	v_readlane_b32 s30, v244, 7
	v_mov_b64_e32 v[36:37], v[28:29]
	v_mov_b64_e32 v[40:41], v[28:29]
	v_mov_b64_e32 v[44:45], v[28:29]
	v_mov_b64_e32 v[48:49], v[28:29]
	v_mov_b64_e32 v[52:53], v[28:29]
	v_mov_b64_e32 v[56:57], v[28:29]
	v_mov_b64_e32 v[60:61], v[28:29]
	v_mov_b64_e32 v[64:65], v[28:29]
	v_mov_b64_e32 v[68:69], v[28:29]
	v_mov_b64_e32 v[72:73], v[28:29]
	v_mov_b64_e32 v[76:77], v[28:29]
	v_mov_b64_e32 v[80:81], v[28:29]
	v_mov_b64_e32 v[84:85], v[28:29]
	v_mov_b64_e32 v[88:89], v[28:29]
	v_mov_b64_e32 v[92:93], v[28:29]
	v_mov_b64_e32 v[96:97], v[28:29]
	v_mov_b32_e32 v116, 0
	v_mov_b32_e32 v218, 0xf149f2ca
	v_mov_b32_e32 v216, 0
	v_mov_b32_e32 v29, 0
	ds_read_b32 v239, v151 offset:9728
	s_waitcnt lgkmcnt(0)
	v_readfirstlane_b32 s32, v239
	s_branch .LBB0_623

.LBB0_623:
	s_add_i32 s0, s30, -8
	v_mov_b32_e32 v30, s0
	ds_read2_b32 v[30:31], v30 offset1:1
	s_add_i32 s0, s31, 1
	s_cmp_lt_i32 s0, s28
	s_cselect_b64 s[18:19], -1, 0
	s_cmp_ge_i32 s0, s28
	s_cselect_b64 s[16:17], -1, 0
	s_waitcnt lgkmcnt(0)
	v_readfirstlane_b32 s2, v30
	v_readfirstlane_b32 s3, v31
	s_ashr_i32 s98, s2, 5
	v_lshl_add_u32 v239, s98, 2, v195
	ds_read_b32 v247, v239 offset:256
	ds_read_b32 v239, v239
	s_and_b64 vcc, exec, s[16:17]
	s_waitcnt vmcnt(0)
	v_mov_b32_e32 v100, 0
	v_mov_b32_e32 v101, 0
	v_mov_b32_e32 v102, 0
	v_mov_b32_e32 v103, 0
	v_mov_b32_e32 v104, 0
	v_mov_b32_e32 v105, 0
	v_mov_b32_e32 v106, 0
	v_mov_b32_e32 v107, 0
	v_mov_b32_e32 v108, 0
	v_mov_b32_e32 v109, 0
	v_mov_b32_e32 v110, 0
	v_mov_b32_e32 v111, 0
	v_mov_b32_e32 v112, 0
	v_mov_b32_e32 v113, 0
	v_mov_b32_e32 v114, 0
	v_mov_b32_e32 v115, 0
	s_cbranch_vccnz .LBB0_625
	s_mul_i32 s0, s3, 0x60000
	s_mul_hi_i32 s1, s3, 0x60000
	s_add_u32 s0, s12, s0
	s_addc_u32 s1, s13, s1
	s_lshl_b32 s8, s3, 6
	s_ashr_i32 s9, s8, 31
	v_lshl_add_u64 v[30:31], v[166:167], 1, s[0:1]
	v_lshl_add_u64 v[100:101], v[168:169], 1, s[0:1]
	s_lshl_b64 s[0:1], s[8:9], 1
	s_add_u32 s0, s14, s0
	s_addc_u32 s1, s15, s1
	global_load_dwordx4 v[104:107], v[30:31], off offset:2048
	global_load_dwordx4 v[108:111], v[100:101], off offset:2048
	v_lshl_add_u64 v[30:31], v[170:171], 1, s[0:1]
	v_lshl_add_u64 v[100:101], v[172:173], 1, s[0:1]
	global_load_dwordx4 v[112:115], v[30:31], off
	s_nop 0
	global_load_dwordx4 v[100:103], v[100:101], off
.LBB0_625:
	s_lshl_b32 s0, 1, s2
	s_waitcnt lgkmcnt(0)
	v_and_b32_e32 v31, s0, v247
	v_and_b32_e32 v30, s0, v239
	v_or_b32_e32 v118, v30, v31
	v_cmp_ne_u32_e64 s[8:9], 0, v31
	v_cmp_ne_u32_e64 s[0:1], 0, v30
	v_cmp_ne_u32_e32 vcc, 0, v118
	s_cbranch_vccz .LBB0_677
	s_lshl_b32 s2, s2, 6
	v_cndmask_b32_e64 v30, 0, 1, s[8:9]
	v_cndmask_b32_e64 v31, 0, 1, s[0:1]
	s_sub_i32 s0, s29, s2
	v_lshlrev_b16_e32 v30, 8, v30
	s_cmpk_lt_i32 s0, 0x80
	v_or_b32_e32 v30, v31, v30
	s_cselect_b64 s[20:21], -1, 0
	s_cmpk_gt_i32 s0, 0x7f
	s_setprio 1
	ds_read_b128 v[174:177], v212
	ds_read_b128 v[240:243], v212 offset:64
	ds_read_b128 v[248:251], v212 offset:128
	ds_read_b128 v[252:255], v212 offset:192
	s_waitcnt lgkmcnt(3)
	v_mfma_f32_16x16x32_bf16 v[132:135], v[174:177], v[0:3], 0
	v_mfma_f32_16x16x32_bf16 v[116:119], v[174:177], v[16:19], 0
	ds_read_b128 v[174:177], v212 offset:4352
	s_waitcnt lgkmcnt(3)
	v_mfma_f32_16x16x32_bf16 v[132:135], v[240:243], v[4:7], v[132:135]
	v_mfma_f32_16x16x32_bf16 v[116:119], v[240:243], v[20:23], v[116:119]
	ds_read_b128 v[240:243], v212 offset:4416
	s_waitcnt lgkmcnt(3)
	v_mfma_f32_16x16x32_bf16 v[132:135], v[248:251], v[8:11], v[132:135]
	v_mfma_f32_16x16x32_bf16 v[116:119], v[248:251], v[24:27], v[116:119]
	ds_read_b128 v[248:251], v212 offset:4480
	s_waitcnt lgkmcnt(3)
	v_mfma_f32_16x16x32_bf16 v[132:135], v[252:255], v[12:15], v[132:135]
	v_mfma_f32_16x16x32_bf16 v[116:119], v[252:255], v[32:35], v[116:119]
	ds_read_b128 v[252:255], v212 offset:4544
	s_waitcnt lgkmcnt(3)
	v_mfma_f32_16x16x32_bf16 v[136:139], v[174:177], v[0:3], 0
	v_mfma_f32_16x16x32_bf16 v[120:123], v[174:177], v[16:19], 0
	ds_read_b128 v[174:177], v212 offset:8704
	s_waitcnt lgkmcnt(3)
	v_mfma_f32_16x16x32_bf16 v[136:139], v[240:243], v[4:7], v[136:139]
	v_mfma_f32_16x16x32_bf16 v[120:123], v[240:243], v[20:23], v[120:123]
	ds_read_b128 v[240:243], v212 offset:8768
	s_waitcnt lgkmcnt(3)
	v_mfma_f32_16x16x32_bf16 v[136:139], v[248:251], v[8:11], v[136:139]
	v_mfma_f32_16x16x32_bf16 v[120:123], v[248:251], v[24:27], v[120:123]
	ds_read_b128 v[248:251], v212 offset:8832
	s_waitcnt lgkmcnt(3)
	v_mfma_f32_16x16x32_bf16 v[136:139], v[252:255], v[12:15], v[136:139]
	v_mfma_f32_16x16x32_bf16 v[120:123], v[252:255], v[32:35], v[120:123]
	ds_read_b128 v[252:255], v212 offset:8896
	s_waitcnt lgkmcnt(3)
	v_mfma_f32_16x16x32_bf16 v[140:143], v[174:177], v[0:3], 0
	v_mfma_f32_16x16x32_bf16 v[124:127], v[174:177], v[16:19], 0
	ds_read_b128 v[174:177], v212 offset:13056
	s_waitcnt lgkmcnt(3)
	v_mfma_f32_16x16x32_bf16 v[140:143], v[240:243], v[4:7], v[140:143]
	v_mfma_f32_16x16x32_bf16 v[124:127], v[240:243], v[20:23], v[124:127]
	ds_read_b128 v[240:243], v212 offset:13120
	s_waitcnt lgkmcnt(3)
	v_mfma_f32_16x16x32_bf16 v[140:143], v[248:251], v[8:11], v[140:143]
	v_mfma_f32_16x16x32_bf16 v[124:127], v[248:251], v[24:27], v[124:127]
	ds_read_b128 v[248:251], v212 offset:13184
	s_waitcnt lgkmcnt(3)
	v_mfma_f32_16x16x32_bf16 v[140:143], v[252:255], v[12:15], v[140:143]
	v_mfma_f32_16x16x32_bf16 v[124:127], v[252:255], v[32:35], v[124:127]
	ds_read_b128 v[252:255], v212 offset:13248
	s_waitcnt lgkmcnt(3)
	v_mfma_f32_16x16x32_bf16 v[144:147], v[174:177], v[0:3], 0
	v_mfma_f32_16x16x32_bf16 v[128:131], v[174:177], v[16:19], 0
	s_waitcnt lgkmcnt(2)
	v_mfma_f32_16x16x32_bf16 v[144:147], v[240:243], v[4:7], v[144:147]
	v_mfma_f32_16x16x32_bf16 v[128:131], v[240:243], v[20:23], v[128:131]
	s_waitcnt lgkmcnt(1)
	v_mfma_f32_16x16x32_bf16 v[144:147], v[248:251], v[8:11], v[144:147]
	v_mfma_f32_16x16x32_bf16 v[128:131], v[248:251], v[24:27], v[128:131]
	s_waitcnt lgkmcnt(0)
	v_mfma_f32_16x16x32_bf16 v[144:147], v[252:255], v[12:15], v[144:147]
	v_mfma_f32_16x16x32_bf16 v[128:131], v[252:255], v[32:35], v[128:131]
	s_setprio 0
	v_add_u32_e32 v237, s2, v209
	s_mov_b64 s[0:1], -1
	v_and_b32_e32 v238, 1, v30
	v_or_b32_e32 v236, 2, v237
	v_or_b32_e32 v220, 3, v237
	s_cbranch_scc1 .LBB0_628
	v_sub_u32_e32 v179, v160, v237
	v_med3_i32 v30, v179, 0, v207
	v_lshl_add_u32 v30, v30, 2, v151
	ds_read_b32 v30, v30 offset:9216
	v_cmp_lt_i32_e64 s[0:1], -1, v179
	v_cmp_eq_u32_e32 vcc, 1, v238
	s_and_b64 s[0:1], s[0:1], vcc
	v_xad_u32 v31, v237, -1, v160
	s_waitcnt lgkmcnt(0)
	v_add_f32_e32 v30, v132, v30
	v_cndmask_b32_e64 v30, v208, v30, s[0:1]
	v_cmp_lt_i32_e64 s[0:1], -1, v31
	v_med3_i32 v31, v31, 0, v207
	v_lshl_add_u32 v31, v31, 2, v151
	ds_read_b32 v31, v31 offset:9216
	s_and_b64 s[0:1], s[0:1], vcc
	v_sub_u32_e32 v174, v160, v236
	v_sub_u32_e32 v175, v160, v220
	v_subrev_u32_e32 v177, 17, v179
	s_waitcnt lgkmcnt(0)
	v_add_f32_e32 v31, v133, v31
	v_cndmask_b32_e64 v31, v208, v31, s[0:1]
	v_cmp_lt_i32_e64 s[0:1], -1, v174
	v_med3_i32 v174, v174, 0, v207
	v_lshl_add_u32 v174, v174, 2, v151
	ds_read_b32 v174, v174 offset:9216
	s_and_b64 s[0:1], s[0:1], vcc
	v_max3_f32 v176, v30, s82, v31
	v_subrev_u32_e32 v180, 18, v179
	v_subrev_u32_e32 v181, 19, v179
	s_waitcnt lgkmcnt(0)
	v_add_f32_e32 v174, v134, v174
	v_cndmask_b32_e64 v174, v208, v174, s[0:1]
	v_cmp_lt_i32_e64 s[0:1], -1, v175
	v_med3_i32 v175, v175, 0, v207
	v_lshl_add_u32 v175, v175, 2, v151
	ds_read_b32 v175, v175 offset:9216
	s_and_b64 s[0:1], s[0:1], vcc
	v_subrev_u32_e32 v182, 32, v179
	v_subrev_u32_e32 v183, 33, v179
	v_subrev_u32_e32 v184, 34, v179
	s_waitcnt lgkmcnt(0)
	v_add_f32_e32 v175, v135, v175
	v_cndmask_b32_e64 v175, v208, v175, s[0:1]
	v_max3_f32 v178, v176, v174, v175
	v_add_u32_e32 v176, -16, v179
	v_cmp_lt_i32_e64 s[0:1], -1, v176
	v_med3_i32 v176, v176, 0, v207
	v_lshl_add_u32 v176, v176, 2, v151
	ds_read_b32 v176, v176 offset:9216
	s_and_b64 s[0:1], s[0:1], vcc
	v_subrev_u32_e32 v185, 35, v179
	v_subrev_u32_e32 v186, 48, v179
	v_subrev_u32_e32 v187, 49, v179
	s_waitcnt lgkmcnt(0)
	v_add_f32_e32 v176, v136, v176
	v_cndmask_b32_e64 v176, v208, v176, s[0:1]
	v_cmp_lt_i32_e64 s[0:1], -1, v177
	v_med3_i32 v177, v177, 0, v207
	v_lshl_add_u32 v177, v177, 2, v151
	ds_read_b32 v177, v177 offset:9216
	s_and_b64 s[0:1], s[0:1], vcc
	s_waitcnt lgkmcnt(0)
	v_add_f32_e32 v177, v137, v177
	v_cndmask_b32_e64 v177, v208, v177, s[0:1]
	v_cmp_lt_i32_e64 s[0:1], -1, v180
	v_med3_i32 v180, v180, 0, v207
	v_lshl_add_u32 v180, v180, 2, v151
	ds_read_b32 v180, v180 offset:9216
	s_and_b64 s[0:1], s[0:1], vcc
	v_max3_f32 v178, v178, v176, v177
	s_waitcnt lgkmcnt(0)
	v_add_f32_e32 v180, v138, v180
	v_cndmask_b32_e64 v180, v208, v180, s[0:1]
	v_cmp_lt_i32_e64 s[0:1], -1, v181
	s_and_b64 s[10:11], s[0:1], vcc
	v_med3_i32 v181, v181, 0, v207
	v_cmp_lt_i32_e64 s[0:1], -1, v182
	v_med3_i32 v182, v182, 0, v207
	v_lshl_add_u32 v181, v181, 2, v151
	v_lshl_add_u32 v182, v182, 2, v151
	ds_read_b32 v181, v181 offset:9216
	ds_read_b32 v182, v182 offset:9216
	s_and_b64 s[0:1], s[0:1], vcc
	s_waitcnt lgkmcnt(1)
	v_add_f32_e32 v181, v139, v181
	s_waitcnt lgkmcnt(0)
	v_add_f32_e32 v182, v140, v182
	v_cndmask_b32_e64 v182, v208, v182, s[0:1]
	v_cmp_lt_i32_e64 s[0:1], -1, v183
	v_med3_i32 v183, v183, 0, v207
	v_lshl_add_u32 v183, v183, 2, v151
	ds_read_b32 v183, v183 offset:9216
	s_and_b64 s[0:1], s[0:1], vcc
	v_cndmask_b32_e64 v181, v208, v181, s[10:11]
	v_max3_f32 v178, v178, v180, v181
	s_waitcnt lgkmcnt(0)
	v_add_f32_e32 v183, v141, v183
	v_cndmask_b32_e64 v183, v208, v183, s[0:1]
	v_cmp_lt_i32_e64 s[0:1], -1, v184
	v_med3_i32 v184, v184, 0, v207
	v_lshl_add_u32 v184, v184, 2, v151
	ds_read_b32 v184, v184 offset:9216
	s_and_b64 s[0:1], s[0:1], vcc
	v_max3_f32 v178, v178, v182, v183
	s_waitcnt lgkmcnt(0)
	v_add_f32_e32 v184, v142, v184
	v_cndmask_b32_e64 v184, v208, v184, s[0:1]
	v_cmp_lt_i32_e64 s[0:1], -1, v185
	v_med3_i32 v185, v185, 0, v207
	v_lshl_add_u32 v185, v185, 2, v151
	ds_read_b32 v185, v185 offset:9216
	s_and_b64 s[0:1], s[0:1], vcc
	s_waitcnt lgkmcnt(0)
	v_add_f32_e32 v185, v143, v185
	v_cndmask_b32_e64 v185, v208, v185, s[0:1]
	v_cmp_lt_i32_e64 s[0:1], -1, v186
	v_med3_i32 v186, v186, 0, v207
	v_lshl_add_u32 v186, v186, 2, v151
	ds_read_b32 v186, v186 offset:9216
	s_and_b64 s[0:1], s[0:1], vcc
	v_max3_f32 v178, v178, v184, v185
	s_waitcnt lgkmcnt(0)
	v_add_f32_e32 v186, v144, v186
	v_cndmask_b32_e64 v186, v208, v186, s[0:1]
	v_cmp_lt_i32_e64 s[0:1], -1, v187
	v_med3_i32 v187, v187, 0, v207
	v_lshl_add_u32 v187, v187, 2, v151
	ds_read_b32 v187, v187 offset:9216
	s_and_b64 s[0:1], s[0:1], vcc
	s_waitcnt lgkmcnt(0)
	v_add_f32_e32 v187, v145, v187
	v_cndmask_b32_e64 v187, v208, v187, s[0:1]
	v_max3_f32 v219, v178, v186, v187
	v_subrev_u32_e32 v178, 50, v179
	v_cmp_lt_i32_e64 s[0:1], -1, v178
	v_med3_i32 v178, v178, 0, v207
	v_lshl_add_u32 v178, v178, 2, v151
	ds_read_b32 v178, v178 offset:9216
	s_and_b64 s[0:1], s[0:1], vcc
	v_subrev_u32_e32 v179, 51, v179
	s_waitcnt lgkmcnt(0)
	v_add_f32_e32 v178, v146, v178
	v_cndmask_b32_e64 v178, v208, v178, s[0:1]
	v_cmp_lt_i32_e64 s[0:1], -1, v179
	v_med3_i32 v179, v179, 0, v207
	v_lshl_add_u32 v179, v179, 2, v151
	ds_read_b32 v179, v179 offset:9216
	s_and_b64 vcc, s[0:1], vcc
	s_mov_b64 s[0:1], 0
	s_waitcnt lgkmcnt(0)
	v_add_f32_e32 v179, v147, v179
	v_cndmask_b32_e32 v179, v208, v179, vcc
	v_max3_f32 v219, v219, v178, v179
.LBB0_628:
	s_andn2_b64 vcc, exec, s[0:1]
	v_cmp_eq_u32_e64 s[10:11], 1, v238
	s_cbranch_vccnz .LBB0_630
	v_mov_b32_e32 v178, s32
	v_pk_add_f32 v[30:31], v[132:133], v[178:179] op_sel_hi:[1,0]
	v_pk_add_f32 v[174:175], v[134:135], v[178:179] op_sel_hi:[1,0]
	v_max3_f32 v132, v30, s82, v31
	v_pk_add_f32 v[176:177], v[136:137], v[178:179] op_sel_hi:[1,0]
	v_max3_f32 v132, v132, v174, v175
	v_pk_add_f32 v[180:181], v[138:139], v[178:179] op_sel_hi:[1,0]
	v_max3_f32 v132, v132, v176, v177
	v_pk_add_f32 v[182:183], v[140:141], v[178:179] op_sel_hi:[1,0]
	v_max3_f32 v132, v132, v180, v181
	v_max3_f32 v132, v132, v182, v183
	v_pk_add_f32 v[184:185], v[142:143], v[178:179] op_sel_hi:[1,0]
	v_pk_add_f32 v[186:187], v[144:145], v[178:179] op_sel_hi:[1,0]
	v_max3_f32 v132, v132, v184, v185
	v_max3_f32 v132, v132, v186, v187
	v_pk_add_f32 v[178:179], v[146:147], v[178:179] op_sel_hi:[1,0]
	s_nop 0
	v_max3_f32 v132, v132, v178, v179
	v_cndmask_b32_e64 v219, v208, v132, s[10:11]

.LBB0_638:
	s_andn2_b64 vcc, exec, s[0:1]
	s_cbranch_vccnz .LBB0_640
	v_mov_b32_e32 v138, s32
	v_pk_add_f32 v[132:133], v[116:117], v[138:139] op_sel_hi:[1,0]
	v_pk_add_f32 v[134:135], v[118:119], v[138:139] op_sel_hi:[1,0]
	v_max3_f32 v116, v132, s82, v133
	v_pk_add_f32 v[136:137], v[120:121], v[138:139] op_sel_hi:[1,0]
	v_max3_f32 v116, v116, v134, v135
	v_pk_add_f32 v[140:141], v[122:123], v[138:139] op_sel_hi:[1,0]
	v_max3_f32 v116, v116, v136, v137
	v_pk_add_f32 v[142:143], v[124:125], v[138:139] op_sel_hi:[1,0]
	v_max3_f32 v116, v116, v140, v141
	v_max3_f32 v116, v116, v142, v143
	v_pk_add_f32 v[144:145], v[126:127], v[138:139] op_sel_hi:[1,0]
	v_pk_add_f32 v[146:147], v[128:129], v[138:139] op_sel_hi:[1,0]
	v_max3_f32 v116, v116, v144, v145
	v_max3_f32 v116, v116, v146, v147
	v_pk_add_f32 v[138:139], v[130:131], v[138:139] op_sel_hi:[1,0]
	s_nop 0
	v_max3_f32 v116, v116, v138, v139
	v_cndmask_b32_e64 v176, v208, v116, s[8:9]

.LBB0_646:
	v_add_f32_e32 v117, v117, v130
	v_fmac_f32_e32 v117, v216, v116
	v_add_f32_e32 v116, v174, v175
	v_fmac_f32_e32 v116, v29, v30
	s_setprio 1
	v_cvt_pk_bf16_f32 v130, v221, v222
	v_cvt_pk_bf16_f32 v131, v223, v224
	v_cvt_pk_bf16_f32 v132, v225, v227
	v_cvt_pk_bf16_f32 v133, v229, v231
	v_cvt_pk_bf16_f32 v118, v118, v119
	v_cvt_pk_bf16_f32 v119, v120, v121
	v_cvt_pk_bf16_f32 v120, v122, v124
	v_cvt_pk_bf16_f32 v121, v126, v128
	v_add_u32_e32 v29, 0x800, v213
	v_add_u32_e32 v30, 0x1000, v213
	v_add_u32_e32 v138, 0x1800, v213
	v_add_u32_e32 v139, 0x2000, v213
	v_add_u32_e32 v140, 0x2800, v213
	v_add_u32_e32 v141, 0x3000, v213
	v_add_u32_e32 v142, 0x3800, v213
	ds_read2_b64 v[134:137], v213 offset1:4
	ds_read2_b64 v[240:243], v29 offset0:32 offset1:36
	ds_read2_b64 v[248:251], v30 offset0:64 offset1:68
	ds_read2_b64 v[252:255], v138 offset0:96 offset1:100
	s_waitcnt lgkmcnt(3)
	v_mfma_f32_16x16x32_bf16 v[96:99], v[134:137], v[130:133], v[96:99]
	v_mfma_f32_16x16x32_bf16 v[64:67], v[134:137], v[118:121], v[64:67]
	ds_read2_b64 v[134:137], v139 offset0:128 offset1:132
	s_waitcnt lgkmcnt(3)
	v_mfma_f32_16x16x32_bf16 v[92:95], v[240:243], v[130:133], v[92:95]
	v_mfma_f32_16x16x32_bf16 v[60:63], v[240:243], v[118:121], v[60:63]
	ds_read2_b64 v[240:243], v140 offset0:160 offset1:164
	s_waitcnt lgkmcnt(3)
	v_mfma_f32_16x16x32_bf16 v[88:91], v[248:251], v[130:133], v[88:91]
	v_mfma_f32_16x16x32_bf16 v[56:59], v[248:251], v[118:121], v[56:59]
	ds_read2_b64 v[248:251], v141 offset0:192 offset1:196
	s_waitcnt lgkmcnt(3)
	v_mfma_f32_16x16x32_bf16 v[84:87], v[252:255], v[130:133], v[84:87]
	v_mfma_f32_16x16x32_bf16 v[52:55], v[252:255], v[118:121], v[52:55]
	ds_read2_b64 v[252:255], v142 offset0:224 offset1:228
	s_waitcnt lgkmcnt(3)
	v_mfma_f32_16x16x32_bf16 v[80:83], v[134:137], v[130:133], v[80:83]
	v_mfma_f32_16x16x32_bf16 v[48:51], v[134:137], v[118:121], v[48:51]
	ds_read2_b64 v[134:137], v213 offset0:8 offset1:12
	s_waitcnt lgkmcnt(3)
	v_mfma_f32_16x16x32_bf16 v[76:79], v[240:243], v[130:133], v[76:79]
	v_mfma_f32_16x16x32_bf16 v[44:47], v[240:243], v[118:121], v[44:47]
	ds_read2_b64 v[240:243], v29 offset0:40 offset1:44
	s_waitcnt lgkmcnt(3)
	v_mfma_f32_16x16x32_bf16 v[72:75], v[248:251], v[130:133], v[72:75]
	v_mfma_f32_16x16x32_bf16 v[40:43], v[248:251], v[118:121], v[40:43]
	ds_read2_b64 v[248:251], v30 offset0:72 offset1:76
	s_waitcnt lgkmcnt(3)
	v_mfma_f32_16x16x32_bf16 v[36:39], v[252:255], v[118:121], v[36:39]
	v_mfma_f32_16x16x32_bf16 v[68:71], v[252:255], v[130:133], v[68:71]
	ds_read2_b64 v[252:255], v138 offset0:104 offset1:108
	v_cvt_pk_bf16_f32 v118, v226, v228
	v_cvt_pk_bf16_f32 v119, v230, v232
	v_cvt_pk_bf16_f32 v120, v233, v234
	v_cvt_pk_bf16_f32 v121, v235, v31
	v_cvt_pk_bf16_f32 v122, v123, v125
	v_cvt_pk_bf16_f32 v123, v127, v176
	v_cvt_pk_bf16_f32 v124, v187, v218
	v_cvt_pk_bf16_f32 v125, v236, v129
	s_nop 1
	s_waitcnt lgkmcnt(3)
	v_mfma_f32_16x16x32_bf16 v[96:99], v[134:137], v[118:121], v[96:99]
	v_mfma_f32_16x16x32_bf16 v[64:67], v[134:137], v[122:125], v[64:67]
	ds_read2_b64 v[134:137], v139 offset0:136 offset1:140
	s_waitcnt lgkmcnt(3)
	v_mfma_f32_16x16x32_bf16 v[92:95], v[240:243], v[118:121], v[92:95]
	v_mfma_f32_16x16x32_bf16 v[60:63], v[240:243], v[122:125], v[60:63]
	ds_read2_b64 v[240:243], v140 offset0:168 offset1:172
	s_waitcnt lgkmcnt(3)
	v_mfma_f32_16x16x32_bf16 v[88:91], v[248:251], v[118:121], v[88:91]
	v_mfma_f32_16x16x32_bf16 v[56:59], v[248:251], v[122:125], v[56:59]
	ds_read2_b64 v[248:251], v141 offset0:200 offset1:204
	s_waitcnt lgkmcnt(3)
	v_mfma_f32_16x16x32_bf16 v[84:87], v[252:255], v[118:121], v[84:87]
	v_mfma_f32_16x16x32_bf16 v[52:55], v[252:255], v[122:125], v[52:55]
	ds_read2_b64 v[252:255], v142 offset0:232 offset1:236
	s_waitcnt lgkmcnt(3)
	v_mfma_f32_16x16x32_bf16 v[80:83], v[134:137], v[118:121], v[80:83]
	v_mfma_f32_16x16x32_bf16 v[48:51], v[134:137], v[122:125], v[48:51]
	s_waitcnt lgkmcnt(2)
	v_mfma_f32_16x16x32_bf16 v[76:79], v[240:243], v[118:121], v[76:79]
	v_mfma_f32_16x16x32_bf16 v[44:47], v[240:243], v[122:125], v[44:47]
	s_waitcnt lgkmcnt(1)
	v_mfma_f32_16x16x32_bf16 v[72:75], v[248:251], v[118:121], v[72:75]
	v_mfma_f32_16x16x32_bf16 v[40:43], v[248:251], v[122:125], v[40:43]
	s_waitcnt lgkmcnt(0)
	v_mfma_f32_16x16x32_bf16 v[68:71], v[252:255], v[118:121], v[68:71]
	v_mfma_f32_16x16x32_bf16 v[36:39], v[252:255], v[122:125], v[36:39]
	s_setprio 0
	v_mov_b32_e32 v29, v116
	v_mov_b32_e32 v216, v117
	s_andn2_b64 vcc, exec, s[18:19]
	s_cbranch_vccnz .LBB0_648

.LBB0_650:
	s_andn2_b64 vcc, exec, s[0:1]
	s_cbranch_vccnz .LBB0_622
	s_add_i32 s0, s30, -4
	v_mov_b32_e32 v30, s0
	ds_read2_b32 v[30:31], v30 offset1:1
	s_add_i32 s31, s31, 2
	s_cmp_lt_i32 s31, s28
	s_waitcnt vmcnt(0)
	v_mov_b32_e32 v100, 0
	s_cselect_b64 s[16:17], -1, 0
	s_waitcnt lgkmcnt(0)
	v_readfirstlane_b32 s2, v30
	v_readfirstlane_b32 s3, v31
	s_ashr_i32 s98, s2, 5
	v_lshl_add_u32 v239, s98, 2, v195
	ds_read_b32 v247, v239 offset:256
	ds_read_b32 v239, v239
	s_cmp_ge_i32 s31, s28
	v_mov_b32_e32 v101, 0
	v_mov_b32_e32 v102, 0
	v_mov_b32_e32 v103, 0
	v_mov_b32_e32 v104, 0
	v_mov_b32_e32 v105, 0
	v_mov_b32_e32 v106, 0
	v_mov_b32_e32 v107, 0
	v_mov_b32_e32 v108, 0
	v_mov_b32_e32 v109, 0
	v_mov_b32_e32 v110, 0
	v_mov_b32_e32 v111, 0
	v_mov_b32_e32 v112, 0
	v_mov_b32_e32 v113, 0
	v_mov_b32_e32 v114, 0
	v_mov_b32_e32 v115, 0
	s_cbranch_scc1 .LBB0_653
	s_mul_i32 s0, s3, 0x60000
	s_mul_hi_i32 s1, s3, 0x60000
	s_add_u32 s0, s12, s0
	s_addc_u32 s1, s13, s1
	s_lshl_b32 s8, s3, 6
	s_ashr_i32 s9, s8, 31
	v_lshl_add_u64 v[30:31], v[166:167], 1, s[0:1]
	v_lshl_add_u64 v[100:101], v[168:169], 1, s[0:1]
	s_lshl_b64 s[0:1], s[8:9], 1
	s_add_u32 s0, s14, s0
	s_addc_u32 s1, s15, s1
	global_load_dwordx4 v[104:107], v[30:31], off offset:2048
	global_load_dwordx4 v[108:111], v[100:101], off offset:2048
	v_lshl_add_u64 v[30:31], v[170:171], 1, s[0:1]
	v_lshl_add_u64 v[100:101], v[172:173], 1, s[0:1]
	global_load_dwordx4 v[112:115], v[30:31], off
	s_nop 0
	global_load_dwordx4 v[100:103], v[100:101], off
.LBB0_653:
	s_lshl_b32 s0, 1, s2
	s_waitcnt lgkmcnt(0)
	v_and_b32_e32 v31, s0, v247
	v_and_b32_e32 v30, s0, v239
	v_or_b32_e32 v118, v30, v31
	v_cmp_ne_u32_e64 s[8:9], 0, v31
	v_cmp_ne_u32_e64 s[0:1], 0, v30
	v_cmp_ne_u32_e32 vcc, 0, v118
	s_cbranch_vccz .LBB0_678
	s_lshl_b32 s2, s2, 6
	v_cndmask_b32_e64 v30, 0, 1, s[8:9]
	v_cndmask_b32_e64 v31, 0, 1, s[0:1]
	s_sub_i32 s0, s29, s2
	v_lshlrev_b16_e32 v30, 8, v30
	s_cmpk_lt_i32 s0, 0x80
	v_or_b32_e32 v30, v31, v30
	s_cselect_b64 s[18:19], -1, 0
	s_cmpk_gt_i32 s0, 0x7f
	s_setprio 1
	ds_read_b128 v[174:177], v214 offset:11328
	ds_read_b128 v[240:243], v214 offset:11392
	ds_read_b128 v[248:251], v214 offset:11456
	ds_read_b128 v[252:255], v214 offset:11520
	s_waitcnt lgkmcnt(3)
	v_mfma_f32_16x16x32_bf16 v[132:135], v[174:177], v[0:3], 0
	v_mfma_f32_16x16x32_bf16 v[116:119], v[174:177], v[16:19], 0
	ds_read_b128 v[174:177], v214 offset:15680
	s_waitcnt lgkmcnt(3)
	v_mfma_f32_16x16x32_bf16 v[132:135], v[240:243], v[4:7], v[132:135]
	v_mfma_f32_16x16x32_bf16 v[116:119], v[240:243], v[20:23], v[116:119]
	ds_read_b128 v[240:243], v214 offset:15744
	s_waitcnt lgkmcnt(3)
	v_mfma_f32_16x16x32_bf16 v[132:135], v[248:251], v[8:11], v[132:135]
	v_mfma_f32_16x16x32_bf16 v[116:119], v[248:251], v[24:27], v[116:119]
	ds_read_b128 v[248:251], v214 offset:15808
	s_waitcnt lgkmcnt(3)
	v_mfma_f32_16x16x32_bf16 v[132:135], v[252:255], v[12:15], v[132:135]
	v_mfma_f32_16x16x32_bf16 v[116:119], v[252:255], v[32:35], v[116:119]
	ds_read_b128 v[252:255], v214 offset:15872
	s_waitcnt lgkmcnt(3)
	v_mfma_f32_16x16x32_bf16 v[136:139], v[174:177], v[0:3], 0
	v_mfma_f32_16x16x32_bf16 v[120:123], v[174:177], v[16:19], 0
	ds_read_b128 v[174:177], v214 offset:20032
	s_waitcnt lgkmcnt(3)
	v_mfma_f32_16x16x32_bf16 v[136:139], v[240:243], v[4:7], v[136:139]
	v_mfma_f32_16x16x32_bf16 v[120:123], v[240:243], v[20:23], v[120:123]
	ds_read_b128 v[240:243], v214 offset:20096
	s_waitcnt lgkmcnt(3)
	v_mfma_f32_16x16x32_bf16 v[136:139], v[248:251], v[8:11], v[136:139]
	v_mfma_f32_16x16x32_bf16 v[120:123], v[248:251], v[24:27], v[120:123]
	ds_read_b128 v[248:251], v214 offset:20160
	s_waitcnt lgkmcnt(3)
	v_mfma_f32_16x16x32_bf16 v[136:139], v[252:255], v[12:15], v[136:139]
	v_mfma_f32_16x16x32_bf16 v[120:123], v[252:255], v[32:35], v[120:123]
	ds_read_b128 v[252:255], v214 offset:20224
	s_waitcnt lgkmcnt(3)
	v_mfma_f32_16x16x32_bf16 v[140:143], v[174:177], v[0:3], 0
	v_mfma_f32_16x16x32_bf16 v[124:127], v[174:177], v[16:19], 0
	ds_read_b128 v[174:177], v214 offset:24384
	s_waitcnt lgkmcnt(3)
	v_mfma_f32_16x16x32_bf16 v[140:143], v[240:243], v[4:7], v[140:143]
	v_mfma_f32_16x16x32_bf16 v[124:127], v[240:243], v[20:23], v[124:127]
	ds_read_b128 v[240:243], v214 offset:24448
	s_waitcnt lgkmcnt(3)
	v_mfma_f32_16x16x32_bf16 v[140:143], v[248:251], v[8:11], v[140:143]
	v_mfma_f32_16x16x32_bf16 v[124:127], v[248:251], v[24:27], v[124:127]
	ds_read_b128 v[248:251], v214 offset:24512
	s_waitcnt lgkmcnt(3)
	v_mfma_f32_16x16x32_bf16 v[140:143], v[252:255], v[12:15], v[140:143]
	v_mfma_f32_16x16x32_bf16 v[124:127], v[252:255], v[32:35], v[124:127]
	ds_read_b128 v[252:255], v214 offset:24576
	s_waitcnt lgkmcnt(3)
	v_mfma_f32_16x16x32_bf16 v[144:147], v[174:177], v[0:3], 0
	v_mfma_f32_16x16x32_bf16 v[128:131], v[174:177], v[16:19], 0
	s_waitcnt lgkmcnt(2)
	v_mfma_f32_16x16x32_bf16 v[144:147], v[240:243], v[4:7], v[144:147]
	v_mfma_f32_16x16x32_bf16 v[128:131], v[240:243], v[20:23], v[128:131]
	s_waitcnt lgkmcnt(1)
	v_mfma_f32_16x16x32_bf16 v[144:147], v[248:251], v[8:11], v[144:147]
	v_mfma_f32_16x16x32_bf16 v[128:131], v[248:251], v[24:27], v[128:131]
	s_waitcnt lgkmcnt(0)
	v_mfma_f32_16x16x32_bf16 v[144:147], v[252:255], v[12:15], v[144:147]
	v_mfma_f32_16x16x32_bf16 v[128:131], v[252:255], v[32:35], v[128:131]
	s_setprio 0
	v_add_u32_e32 v237, s2, v209
	s_mov_b64 s[0:1], -1
	v_and_b32_e32 v238, 1, v30
	v_or_b32_e32 v236, 2, v237
	v_or_b32_e32 v217, 3, v237
	s_cbranch_scc1 .LBB0_656
	v_sub_u32_e32 v179, v160, v237
	v_med3_i32 v30, v179, 0, v207
	v_lshl_add_u32 v30, v30, 2, v151
	ds_read_b32 v30, v30 offset:9216
	v_cmp_lt_i32_e64 s[0:1], -1, v179
	v_cmp_eq_u32_e32 vcc, 1, v238
	s_and_b64 s[0:1], s[0:1], vcc
	v_xad_u32 v31, v237, -1, v160
	s_waitcnt lgkmcnt(0)
	v_add_f32_e32 v30, v132, v30
	v_cndmask_b32_e64 v30, v208, v30, s[0:1]
	v_cmp_lt_i32_e64 s[0:1], -1, v31
	v_med3_i32 v31, v31, 0, v207
	v_lshl_add_u32 v31, v31, 2, v151
	ds_read_b32 v31, v31 offset:9216
	s_and_b64 s[0:1], s[0:1], vcc
	v_sub_u32_e32 v174, v160, v236
	v_sub_u32_e32 v175, v160, v217
	v_subrev_u32_e32 v177, 17, v179
	s_waitcnt lgkmcnt(0)
	v_add_f32_e32 v31, v133, v31
	v_cndmask_b32_e64 v31, v208, v31, s[0:1]
	v_cmp_lt_i32_e64 s[0:1], -1, v174
	v_med3_i32 v174, v174, 0, v207
	v_lshl_add_u32 v174, v174, 2, v151
	ds_read_b32 v174, v174 offset:9216
	s_and_b64 s[0:1], s[0:1], vcc
	v_max3_f32 v176, v30, s82, v31
	v_subrev_u32_e32 v180, 18, v179
	v_subrev_u32_e32 v181, 19, v179
	s_waitcnt lgkmcnt(0)
	v_add_f32_e32 v174, v134, v174
	v_cndmask_b32_e64 v174, v208, v174, s[0:1]
	v_cmp_lt_i32_e64 s[0:1], -1, v175
	v_med3_i32 v175, v175, 0, v207
	v_lshl_add_u32 v175, v175, 2, v151
	ds_read_b32 v175, v175 offset:9216
	s_and_b64 s[0:1], s[0:1], vcc
	v_subrev_u32_e32 v182, 32, v179
	v_subrev_u32_e32 v183, 33, v179
	v_subrev_u32_e32 v184, 34, v179
	s_waitcnt lgkmcnt(0)
	v_add_f32_e32 v175, v135, v175
	v_cndmask_b32_e64 v175, v208, v175, s[0:1]
	v_max3_f32 v178, v176, v174, v175
	v_add_u32_e32 v176, -16, v179
	v_cmp_lt_i32_e64 s[0:1], -1, v176
	v_med3_i32 v176, v176, 0, v207
	v_lshl_add_u32 v176, v176, 2, v151
	ds_read_b32 v176, v176 offset:9216
	s_and_b64 s[0:1], s[0:1], vcc
	v_subrev_u32_e32 v185, 35, v179
	v_subrev_u32_e32 v186, 48, v179
	v_subrev_u32_e32 v187, 49, v179
	s_waitcnt lgkmcnt(0)
	v_add_f32_e32 v176, v136, v176
	v_cndmask_b32_e64 v176, v208, v176, s[0:1]
	v_cmp_lt_i32_e64 s[0:1], -1, v177
	v_med3_i32 v177, v177, 0, v207
	v_lshl_add_u32 v177, v177, 2, v151
	ds_read_b32 v177, v177 offset:9216
	s_and_b64 s[0:1], s[0:1], vcc
	s_waitcnt lgkmcnt(0)
	v_add_f32_e32 v177, v137, v177
	v_cndmask_b32_e64 v177, v208, v177, s[0:1]
	v_cmp_lt_i32_e64 s[0:1], -1, v180
	v_med3_i32 v180, v180, 0, v207
	v_lshl_add_u32 v180, v180, 2, v151
	ds_read_b32 v180, v180 offset:9216
	s_and_b64 s[0:1], s[0:1], vcc
	v_max3_f32 v178, v178, v176, v177
	s_waitcnt lgkmcnt(0)
	v_add_f32_e32 v180, v138, v180
	v_cndmask_b32_e64 v180, v208, v180, s[0:1]
	v_cmp_lt_i32_e64 s[0:1], -1, v181
	s_and_b64 s[10:11], s[0:1], vcc
	v_med3_i32 v181, v181, 0, v207
	v_cmp_lt_i32_e64 s[0:1], -1, v182
	v_med3_i32 v182, v182, 0, v207
	v_lshl_add_u32 v181, v181, 2, v151
	v_lshl_add_u32 v182, v182, 2, v151
	ds_read_b32 v181, v181 offset:9216
	ds_read_b32 v182, v182 offset:9216
	s_and_b64 s[0:1], s[0:1], vcc
	s_waitcnt lgkmcnt(1)
	v_add_f32_e32 v181, v139, v181
	s_waitcnt lgkmcnt(0)
	v_add_f32_e32 v182, v140, v182
	v_cndmask_b32_e64 v182, v208, v182, s[0:1]
	v_cmp_lt_i32_e64 s[0:1], -1, v183
	v_med3_i32 v183, v183, 0, v207
	v_lshl_add_u32 v183, v183, 2, v151
	ds_read_b32 v183, v183 offset:9216
	s_and_b64 s[0:1], s[0:1], vcc
	v_cndmask_b32_e64 v181, v208, v181, s[10:11]
	v_max3_f32 v178, v178, v180, v181
	s_waitcnt lgkmcnt(0)
	v_add_f32_e32 v183, v141, v183
	v_cndmask_b32_e64 v183, v208, v183, s[0:1]
	v_cmp_lt_i32_e64 s[0:1], -1, v184
	v_med3_i32 v184, v184, 0, v207
	v_lshl_add_u32 v184, v184, 2, v151
	ds_read_b32 v184, v184 offset:9216
	s_and_b64 s[0:1], s[0:1], vcc
	v_max3_f32 v178, v178, v182, v183
	s_waitcnt lgkmcnt(0)
	v_add_f32_e32 v184, v142, v184
	v_cndmask_b32_e64 v184, v208, v184, s[0:1]
	v_cmp_lt_i32_e64 s[0:1], -1, v185
	v_med3_i32 v185, v185, 0, v207
	v_lshl_add_u32 v185, v185, 2, v151
	ds_read_b32 v185, v185 offset:9216
	s_and_b64 s[0:1], s[0:1], vcc
	s_waitcnt lgkmcnt(0)
	v_add_f32_e32 v185, v143, v185
	v_cndmask_b32_e64 v185, v208, v185, s[0:1]
	v_cmp_lt_i32_e64 s[0:1], -1, v186
	v_med3_i32 v186, v186, 0, v207
	v_lshl_add_u32 v186, v186, 2, v151
	ds_read_b32 v186, v186 offset:9216
	s_and_b64 s[0:1], s[0:1], vcc
	v_max3_f32 v178, v178, v184, v185
	s_waitcnt lgkmcnt(0)
	v_add_f32_e32 v186, v144, v186
	v_cndmask_b32_e64 v186, v208, v186, s[0:1]
	v_cmp_lt_i32_e64 s[0:1], -1, v187
	v_med3_i32 v187, v187, 0, v207
	v_lshl_add_u32 v187, v187, 2, v151
	ds_read_b32 v187, v187 offset:9216
	s_and_b64 s[0:1], s[0:1], vcc
	s_waitcnt lgkmcnt(0)
	v_add_f32_e32 v187, v145, v187
	v_cndmask_b32_e64 v187, v208, v187, s[0:1]
	v_max3_f32 v218, v178, v186, v187
	v_subrev_u32_e32 v178, 50, v179
	v_cmp_lt_i32_e64 s[0:1], -1, v178
	v_med3_i32 v178, v178, 0, v207
	v_lshl_add_u32 v178, v178, 2, v151
	ds_read_b32 v178, v178 offset:9216
	s_and_b64 s[0:1], s[0:1], vcc
	v_subrev_u32_e32 v179, 51, v179
	s_waitcnt lgkmcnt(0)
	v_add_f32_e32 v178, v146, v178
	v_cndmask_b32_e64 v178, v208, v178, s[0:1]
	v_cmp_lt_i32_e64 s[0:1], -1, v179
	v_med3_i32 v179, v179, 0, v207
	v_lshl_add_u32 v179, v179, 2, v151
	ds_read_b32 v179, v179 offset:9216
	s_and_b64 vcc, s[0:1], vcc
	s_mov_b64 s[0:1], 0
	s_waitcnt lgkmcnt(0)
	v_add_f32_e32 v179, v147, v179
	v_cndmask_b32_e32 v179, v208, v179, vcc
	v_max3_f32 v218, v218, v178, v179
.LBB0_656:
	s_andn2_b64 vcc, exec, s[0:1]
	v_cmp_eq_u32_e64 s[10:11], 1, v238
	s_cbranch_vccnz .LBB0_658
	v_mov_b32_e32 v178, s32
	v_pk_add_f32 v[30:31], v[132:133], v[178:179] op_sel_hi:[1,0]
	v_pk_add_f32 v[174:175], v[134:135], v[178:179] op_sel_hi:[1,0]
	v_max3_f32 v132, v30, s82, v31
	v_pk_add_f32 v[176:177], v[136:137], v[178:179] op_sel_hi:[1,0]
	v_max3_f32 v132, v132, v174, v175
	v_pk_add_f32 v[180:181], v[138:139], v[178:179] op_sel_hi:[1,0]
	v_max3_f32 v132, v132, v176, v177
	v_pk_add_f32 v[182:183], v[140:141], v[178:179] op_sel_hi:[1,0]
	v_max3_f32 v132, v132, v180, v181
	v_max3_f32 v132, v132, v182, v183
	v_pk_add_f32 v[184:185], v[142:143], v[178:179] op_sel_hi:[1,0]
	v_pk_add_f32 v[186:187], v[144:145], v[178:179] op_sel_hi:[1,0]
	v_max3_f32 v132, v132, v184, v185
	v_max3_f32 v132, v132, v186, v187
	v_pk_add_f32 v[178:179], v[146:147], v[178:179] op_sel_hi:[1,0]
	s_nop 0
	v_max3_f32 v132, v132, v178, v179
	v_cndmask_b32_e64 v218, v208, v132, s[10:11]

.LBB0_674:
	v_add_f32_e32 v117, v117, v130
	v_fmac_f32_e32 v117, v216, v116
	v_add_f32_e32 v116, v174, v175
	v_fmac_f32_e32 v116, v29, v30
	s_setprio 1
	v_cvt_pk_bf16_f32 v132, v221, v222
	v_cvt_pk_bf16_f32 v133, v223, v224
	v_cvt_pk_bf16_f32 v134, v225, v227
	v_cvt_pk_bf16_f32 v135, v229, v231
	v_cvt_pk_bf16_f32 v118, v118, v119
	v_cvt_pk_bf16_f32 v119, v120, v121
	v_cvt_pk_bf16_f32 v120, v122, v124
	v_cvt_pk_bf16_f32 v121, v126, v128
	v_add_u32_e32 v29, 0x7000, v215
	v_add_u32_e32 v30, 0x7800, v215
	v_add_u32_e32 v130, 0x8000, v215
	v_add_u32_e32 v140, 0x8800, v215
	v_add_u32_e32 v141, 0x9000, v215
	v_add_u32_e32 v142, 0x9800, v215
	v_add_u32_e32 v143, 0xa000, v215
	v_add_u32_e32 v144, 0xa800, v215
	ds_read2_b64 v[136:139], v29 offset0:8 offset1:12
	ds_read2_b64 v[240:243], v30 offset0:40 offset1:44
	ds_read2_b64 v[248:251], v130 offset0:72 offset1:76
	ds_read2_b64 v[252:255], v140 offset0:104 offset1:108
	s_waitcnt lgkmcnt(3)
	v_mfma_f32_16x16x32_bf16 v[96:99], v[136:139], v[132:135], v[96:99]
	v_mfma_f32_16x16x32_bf16 v[64:67], v[136:139], v[118:121], v[64:67]
	ds_read2_b64 v[136:139], v141 offset0:136 offset1:140
	s_waitcnt lgkmcnt(3)
	v_mfma_f32_16x16x32_bf16 v[92:95], v[240:243], v[132:135], v[92:95]
	v_mfma_f32_16x16x32_bf16 v[60:63], v[240:243], v[118:121], v[60:63]
	ds_read2_b64 v[240:243], v142 offset0:168 offset1:172
	s_waitcnt lgkmcnt(3)
	v_mfma_f32_16x16x32_bf16 v[88:91], v[248:251], v[132:135], v[88:91]
	v_mfma_f32_16x16x32_bf16 v[56:59], v[248:251], v[118:121], v[56:59]
	ds_read2_b64 v[248:251], v143 offset0:200 offset1:204
	s_waitcnt lgkmcnt(3)
	v_mfma_f32_16x16x32_bf16 v[84:87], v[252:255], v[132:135], v[84:87]
	v_mfma_f32_16x16x32_bf16 v[52:55], v[252:255], v[118:121], v[52:55]
	ds_read2_b64 v[252:255], v144 offset0:232 offset1:236
	s_waitcnt lgkmcnt(3)
	v_mfma_f32_16x16x32_bf16 v[80:83], v[136:139], v[132:135], v[80:83]
	v_mfma_f32_16x16x32_bf16 v[48:51], v[136:139], v[118:121], v[48:51]
	ds_read2_b64 v[136:139], v29 offset0:16 offset1:20
	s_waitcnt lgkmcnt(3)
	v_mfma_f32_16x16x32_bf16 v[76:79], v[240:243], v[132:135], v[76:79]
	v_mfma_f32_16x16x32_bf16 v[44:47], v[240:243], v[118:121], v[44:47]
	ds_read2_b64 v[240:243], v30 offset0:48 offset1:52
	s_waitcnt lgkmcnt(3)
	v_mfma_f32_16x16x32_bf16 v[72:75], v[248:251], v[132:135], v[72:75]
	v_mfma_f32_16x16x32_bf16 v[40:43], v[248:251], v[118:121], v[40:43]
	ds_read2_b64 v[248:251], v130 offset0:80 offset1:84
	s_waitcnt lgkmcnt(3)
	v_mfma_f32_16x16x32_bf16 v[36:39], v[252:255], v[118:121], v[36:39]
	v_mfma_f32_16x16x32_bf16 v[68:71], v[252:255], v[132:135], v[68:71]
	ds_read2_b64 v[252:255], v140 offset0:112 offset1:116
	v_cvt_pk_bf16_f32 v118, v226, v228
	v_cvt_pk_bf16_f32 v119, v230, v232
	v_cvt_pk_bf16_f32 v120, v233, v234
	v_cvt_pk_bf16_f32 v121, v235, v31
	v_cvt_pk_bf16_f32 v122, v123, v125
	v_cvt_pk_bf16_f32 v123, v127, v131
	v_cvt_pk_bf16_f32 v124, v187, v219
	v_cvt_pk_bf16_f32 v125, v236, v129
	s_nop 1
	s_waitcnt lgkmcnt(3)
	v_mfma_f32_16x16x32_bf16 v[96:99], v[136:139], v[118:121], v[96:99]
	v_mfma_f32_16x16x32_bf16 v[64:67], v[136:139], v[122:125], v[64:67]
	ds_read2_b64 v[136:139], v141 offset0:144 offset1:148
	s_waitcnt lgkmcnt(3)
	v_mfma_f32_16x16x32_bf16 v[92:95], v[240:243], v[118:121], v[92:95]
	v_mfma_f32_16x16x32_bf16 v[60:63], v[240:243], v[122:125], v[60:63]
	ds_read2_b64 v[240:243], v142 offset0:176 offset1:180
	s_waitcnt lgkmcnt(3)
	v_mfma_f32_16x16x32_bf16 v[88:91], v[248:251], v[118:121], v[88:91]
	v_mfma_f32_16x16x32_bf16 v[56:59], v[248:251], v[122:125], v[56:59]
	ds_read2_b64 v[248:251], v143 offset0:208 offset1:212
	s_waitcnt lgkmcnt(3)
	v_mfma_f32_16x16x32_bf16 v[84:87], v[252:255], v[118:121], v[84:87]
	v_mfma_f32_16x16x32_bf16 v[52:55], v[252:255], v[122:125], v[52:55]
	ds_read2_b64 v[252:255], v144 offset0:240 offset1:244
	s_waitcnt lgkmcnt(3)
	v_mfma_f32_16x16x32_bf16 v[80:83], v[136:139], v[118:121], v[80:83]
	v_mfma_f32_16x16x32_bf16 v[48:51], v[136:139], v[122:125], v[48:51]
	s_waitcnt lgkmcnt(2)
	v_mfma_f32_16x16x32_bf16 v[76:79], v[240:243], v[118:121], v[76:79]
	v_mfma_f32_16x16x32_bf16 v[44:47], v[240:243], v[122:125], v[44:47]
	s_waitcnt lgkmcnt(1)
	v_mfma_f32_16x16x32_bf16 v[72:75], v[248:251], v[118:121], v[72:75]
	v_mfma_f32_16x16x32_bf16 v[40:43], v[248:251], v[122:125], v[40:43]
	s_waitcnt lgkmcnt(0)
	v_mfma_f32_16x16x32_bf16 v[68:71], v[252:255], v[118:121], v[68:71]
	v_mfma_f32_16x16x32_bf16 v[36:39], v[252:255], v[122:125], v[36:39]
	s_setprio 0
	v_mov_b32_e32 v29, v116
	v_mov_b32_e32 v216, v117
	s_andn2_b64 vcc, exec, s[16:17]
	s_cbranch_vccnz .LBB0_676

.LBB0_693:
	s_setprio 1
	ds_read_b128 v[188:191], v176
	ds_read_b128 v[240:243], v176 offset:64
	ds_read_b128 v[248:251], v176 offset:128
	ds_read_b128 v[252:255], v176 offset:192
	s_waitcnt lgkmcnt(3)
	v_mfma_f32_16x16x32_bf16 v[184:187], v[188:191], v[0:3], 0
	v_mfma_f32_16x16x32_bf16 v[128:131], v[188:191], v[16:19], 0
	ds_read_b128 v[188:191], v176 offset:4352
	s_waitcnt lgkmcnt(3)
	v_mfma_f32_16x16x32_bf16 v[184:187], v[240:243], v[4:7], v[184:187]
	v_mfma_f32_16x16x32_bf16 v[128:131], v[240:243], v[20:23], v[128:131]
	ds_read_b128 v[240:243], v176 offset:4416
	s_waitcnt lgkmcnt(3)
	v_mfma_f32_16x16x32_bf16 v[184:187], v[248:251], v[8:11], v[184:187]
	v_mfma_f32_16x16x32_bf16 v[128:131], v[248:251], v[24:27], v[128:131]
	ds_read_b128 v[248:251], v176 offset:4480
	s_waitcnt lgkmcnt(3)
	v_mfma_f32_16x16x32_bf16 v[184:187], v[252:255], v[12:15], v[184:187]
	v_mfma_f32_16x16x32_bf16 v[128:131], v[252:255], v[32:35], v[128:131]
	ds_read_b128 v[252:255], v176 offset:4544
	s_waitcnt lgkmcnt(3)
	v_mfma_f32_16x16x32_bf16 v[140:143], v[188:191], v[0:3], 0
	v_mfma_f32_16x16x32_bf16 v[124:127], v[188:191], v[16:19], 0
	ds_read_b128 v[188:191], v176 offset:8704
	s_waitcnt lgkmcnt(3)
	v_mfma_f32_16x16x32_bf16 v[140:143], v[240:243], v[4:7], v[140:143]
	v_mfma_f32_16x16x32_bf16 v[124:127], v[240:243], v[20:23], v[124:127]
	ds_read_b128 v[240:243], v176 offset:8768
	s_waitcnt lgkmcnt(3)
	v_mfma_f32_16x16x32_bf16 v[140:143], v[248:251], v[8:11], v[140:143]
	v_mfma_f32_16x16x32_bf16 v[124:127], v[248:251], v[24:27], v[124:127]
	ds_read_b128 v[248:251], v176 offset:8832
	s_waitcnt lgkmcnt(3)
	v_mfma_f32_16x16x32_bf16 v[140:143], v[252:255], v[12:15], v[140:143]
	v_mfma_f32_16x16x32_bf16 v[124:127], v[252:255], v[32:35], v[124:127]
	ds_read_b128 v[252:255], v176 offset:8896
	s_waitcnt lgkmcnt(3)
	v_mfma_f32_16x16x32_bf16 v[136:139], v[188:191], v[0:3], 0
	v_mfma_f32_16x16x32_bf16 v[120:123], v[188:191], v[16:19], 0
	ds_read_b128 v[188:191], v176 offset:13056
	s_waitcnt lgkmcnt(3)
	v_mfma_f32_16x16x32_bf16 v[136:139], v[240:243], v[4:7], v[136:139]
	v_mfma_f32_16x16x32_bf16 v[120:123], v[240:243], v[20:23], v[120:123]
	ds_read_b128 v[240:243], v176 offset:13120
	s_waitcnt lgkmcnt(3)
	v_mfma_f32_16x16x32_bf16 v[136:139], v[248:251], v[8:11], v[136:139]
	v_mfma_f32_16x16x32_bf16 v[120:123], v[248:251], v[24:27], v[120:123]
	ds_read_b128 v[248:251], v176 offset:13184
	s_waitcnt lgkmcnt(3)
	v_mfma_f32_16x16x32_bf16 v[136:139], v[252:255], v[12:15], v[136:139]
	v_mfma_f32_16x16x32_bf16 v[120:123], v[252:255], v[32:35], v[120:123]
	ds_read_b128 v[252:255], v176 offset:13248
	s_waitcnt lgkmcnt(3)
	v_mfma_f32_16x16x32_bf16 v[132:135], v[188:191], v[0:3], 0
	v_mfma_f32_16x16x32_bf16 v[116:119], v[188:191], v[16:19], 0
	s_waitcnt lgkmcnt(2)
	v_mfma_f32_16x16x32_bf16 v[132:135], v[240:243], v[4:7], v[132:135]
	v_mfma_f32_16x16x32_bf16 v[116:119], v[240:243], v[20:23], v[116:119]
	s_waitcnt lgkmcnt(1)
	v_mfma_f32_16x16x32_bf16 v[132:135], v[248:251], v[8:11], v[132:135]
	v_mfma_f32_16x16x32_bf16 v[116:119], v[248:251], v[24:27], v[116:119]
	s_waitcnt lgkmcnt(0)
	v_mfma_f32_16x16x32_bf16 v[132:135], v[252:255], v[12:15], v[132:135]
	v_mfma_f32_16x16x32_bf16 v[116:119], v[252:255], v[32:35], v[116:119]
	s_setprio 0
	v_lshl_add_u32 v189, s2, 6, v155
	v_or_b32_e32 v190, 1, v189
	v_sub_u32_e32 v30, v160, v189
	v_sub_u32_e32 v183, v160, v190
	v_cmp_gt_u32_e64 s[8:9], s75, v30
	v_med3_i32 v30, v30, 0, v207
	v_cmp_gt_u32_e32 vcc, s75, v183
	v_med3_i32 v183, v183, 0, v207
	v_lshl_add_u32 v30, v30, 2, v151
	v_lshl_add_u32 v183, v183, 2, v151
	ds_read_b32 v31, v30 offset:9216
	ds_read_b32 v183, v183 offset:9216
	v_or_b32_e32 v191, 2, v189
	v_or_b32_e32 v192, 3, v189
	v_add_u32_e32 v213, 17, v189
	s_waitcnt lgkmcnt(1)
	v_add_f32_e32 v30, v184, v31
	s_waitcnt lgkmcnt(0)
	v_add_f32_e32 v183, v185, v183
	v_sub_u32_e32 v185, v160, v191
	v_cndmask_b32_e32 v184, v208, v183, vcc
	v_cmp_gt_u32_e32 vcc, s75, v185
	v_med3_i32 v185, v185, 0, v207
	v_lshl_add_u32 v185, v185, 2, v151
	ds_read_b32 v185, v185 offset:9216
	v_add_u32_e32 v214, 18, v189
	v_add_u32_e32 v215, 19, v189
	v_add_u32_e32 v216, 32, v189
	v_add_u32_e32 v193, 33, v189
	s_waitcnt lgkmcnt(0)
	v_add_f32_e32 v185, v186, v185
	v_sub_u32_e32 v186, v160, v192
	v_cndmask_b32_e32 v185, v208, v185, vcc
	v_cmp_gt_u32_e32 vcc, s75, v186
	v_med3_i32 v186, v186, 0, v207
	v_lshl_add_u32 v186, v186, 2, v151
	ds_read_b32 v186, v186 offset:9216
	v_cndmask_b32_e64 v30, v208, v30, s[8:9]
	v_max3_f32 v183, v30, s82, v184
	v_add_u32_e32 v194, 34, v189
	v_add_u32_e32 v195, 35, v189
	s_waitcnt lgkmcnt(0)
	v_add_f32_e32 v186, v187, v186
	v_sub_u32_e32 v187, v175, v189
	v_cndmask_b32_e32 v186, v208, v186, vcc
	v_cmp_gt_u32_e32 vcc, s75, v187
	v_med3_i32 v187, v187, 0, v207
	v_lshl_add_u32 v187, v187, 2, v151
	ds_read_b32 v187, v187 offset:9216
	v_max3_f32 v183, v183, v185, v186
	v_add_u32_e32 v209, 48, v189
	v_add_u32_e32 v210, 49, v189
	v_add_u32_e32 v211, 50, v189
	s_waitcnt lgkmcnt(0)
	v_add_f32_e32 v140, v140, v187
	v_sub_u32_e32 v187, v160, v213
	v_cndmask_b32_e32 v140, v208, v140, vcc
	v_cmp_gt_u32_e32 vcc, s75, v187
	v_med3_i32 v187, v187, 0, v207
	v_lshl_add_u32 v187, v187, 2, v151
	ds_read_b32 v187, v187 offset:9216
	v_add_u32_e32 v212, 51, v189
	s_waitcnt lgkmcnt(0)
	v_add_f32_e32 v141, v141, v187
	v_sub_u32_e32 v187, v160, v214
	v_cndmask_b32_e32 v141, v208, v141, vcc
	v_cmp_gt_u32_e32 vcc, s75, v187
	v_med3_i32 v187, v187, 0, v207
	v_lshl_add_u32 v187, v187, 2, v151
	ds_read_b32 v187, v187 offset:9216
	v_max3_f32 v183, v183, v140, v141
	s_waitcnt lgkmcnt(0)
	v_add_f32_e32 v142, v142, v187
	v_sub_u32_e32 v187, v160, v215
	v_cndmask_b32_e32 v142, v208, v142, vcc
	v_cmp_gt_u32_e32 vcc, s75, v187
	v_med3_i32 v187, v187, 0, v207
	v_lshl_add_u32 v187, v187, 2, v151
	ds_read_b32 v187, v187 offset:9216
	s_waitcnt lgkmcnt(0)
	v_add_f32_e32 v143, v143, v187
	v_sub_u32_e32 v187, v160, v216
	v_cndmask_b32_e32 v143, v208, v143, vcc
	v_cmp_gt_u32_e32 vcc, s75, v187
	v_med3_i32 v187, v187, 0, v207
	v_lshl_add_u32 v187, v187, 2, v151
	ds_read_b32 v187, v187 offset:9216
	v_max3_f32 v183, v183, v142, v143
	s_waitcnt lgkmcnt(0)
	v_add_f32_e32 v136, v136, v187
	v_sub_u32_e32 v187, v160, v193
	v_cndmask_b32_e32 v136, v208, v136, vcc
	v_cmp_gt_u32_e32 vcc, s75, v187
	v_med3_i32 v187, v187, 0, v207
	v_lshl_add_u32 v187, v187, 2, v151
	ds_read_b32 v187, v187 offset:9216
	s_waitcnt lgkmcnt(0)
	v_add_f32_e32 v137, v137, v187
	v_cndmask_b32_e32 v187, v208, v137, vcc
	v_max3_f32 v137, v183, v136, v187
	v_sub_u32_e32 v183, v160, v194
	v_cmp_gt_u32_e32 vcc, s75, v183
	v_med3_i32 v183, v183, 0, v207
	v_lshl_add_u32 v183, v183, 2, v151
	ds_read_b32 v183, v183 offset:9216
	s_waitcnt lgkmcnt(0)
	v_add_f32_e32 v138, v138, v183
	v_cndmask_b32_e32 v188, v208, v138, vcc
	v_sub_u32_e32 v138, v160, v195
	v_cmp_gt_u32_e32 vcc, s75, v138
	v_med3_i32 v138, v138, 0, v207
	v_lshl_add_u32 v138, v138, 2, v151
	ds_read_b32 v138, v138 offset:9216
	s_waitcnt lgkmcnt(0)
	v_add_f32_e32 v138, v139, v138
	v_cndmask_b32_e32 v217, v208, v138, vcc
	v_sub_u32_e32 v138, v160, v209
	v_cmp_gt_u32_e32 vcc, s75, v138
	v_med3_i32 v138, v138, 0, v207
	v_lshl_add_u32 v138, v138, 2, v151
	ds_read_b32 v138, v138 offset:9216
	v_max3_f32 v137, v137, v188, v217
	s_waitcnt lgkmcnt(0)
	v_add_f32_e32 v132, v132, v138
	v_cndmask_b32_e32 v218, v208, v132, vcc
	v_sub_u32_e32 v132, v160, v210
	v_cmp_gt_u32_e32 vcc, s75, v132
	v_med3_i32 v132, v132, 0, v207
	v_lshl_add_u32 v132, v132, 2, v151
	ds_read_b32 v132, v132 offset:9216
	s_waitcnt lgkmcnt(0)
	v_add_f32_e32 v132, v133, v132
	v_sub_u32_e32 v133, v160, v211
	v_cndmask_b32_e32 v219, v208, v132, vcc
	v_cmp_gt_u32_e32 vcc, s75, v133
	v_med3_i32 v133, v133, 0, v207
	v_lshl_add_u32 v133, v133, 2, v151
	ds_read_b32 v133, v133 offset:9216
	v_max3_f32 v132, v137, v218, v219
	s_waitcnt lgkmcnt(0)
	v_add_f32_e32 v133, v134, v133
	v_cndmask_b32_e32 v220, v208, v133, vcc
	v_sub_u32_e32 v133, v160, v212
	v_cmp_gt_u32_e32 vcc, s75, v133
	v_med3_i32 v133, v133, 0, v207
	v_lshl_add_u32 v133, v133, 2, v151
	ds_read_b32 v133, v133 offset:9216
	s_waitcnt lgkmcnt(0)
	v_add_f32_e32 v133, v135, v133
	v_cndmask_b32_e32 v135, v208, v133, vcc
	v_max3_f32 v132, v132, v220, v135
	v_mov_b32_e32 v133, v132
	s_nop 1
	v_permlane16_swap_b32_e32 v132, v133
	v_max_f32_e32 v133, v133, v133
	v_max_f32_e32 v132, v132, v132
	v_max_f32_e32 v132, v132, v133
	v_mov_b32_e32 v133, v132
	s_nop 1
	v_permlane32_swap_b32_e32 v132, v133
	v_max3_f32 v183, v29, v132, v133
	v_sub_f32_e32 v29, v29, v183
	v_mul_f32_e32 v221, 0x3fb8aa3b, v29
	v_sub_f32_e32 v29, v30, v183
	v_mul_f32_e32 v29, 0x3fb8aa3b, v29
	v_sub_f32_e32 v132, v184, v183
	v_exp_f32_e32 v29, v29
	v_mul_f32_e32 v132, 0x3fb8aa3b, v132
	v_sub_f32_e32 v133, v185, v183
	v_exp_f32_e32 v132, v132
	v_mul_f32_e32 v133, 0x3fb8aa3b, v133
	v_sub_f32_e32 v134, v186, v183
	v_exp_f32_e32 v133, v133
	v_mul_f32_e32 v134, 0x3fb8aa3b, v134
	v_cmp_lt_f32_e32 vcc, s51, v30
	v_exp_f32_e32 v134, v134
	s_nop 0
	v_cndmask_b32_e32 v29, 0, v29, vcc
	v_cmp_lt_f32_e32 vcc, s51, v184
	v_add_f32_e32 v30, 0, v29
	s_nop 0
	v_cndmask_b32_e32 v132, 0, v132, vcc
	v_cmp_lt_f32_e32 vcc, s51, v185
	v_add_f32_e32 v30, v132, v30
	s_nop 0
	v_cndmask_b32_e32 v133, 0, v133, vcc
	v_cmp_lt_f32_e32 vcc, s51, v186
	v_add_f32_e32 v30, v133, v30
	s_nop 0
	v_cndmask_b32_e32 v137, 0, v134, vcc
	v_sub_f32_e32 v134, v140, v183
	v_mul_f32_e32 v134, 0x3fb8aa3b, v134
	v_exp_f32_e32 v134, v134
	v_cmp_lt_f32_e32 vcc, s51, v140
	v_add_f32_e32 v30, v137, v30
	s_nop 0
	v_cndmask_b32_e32 v138, 0, v134, vcc
	v_sub_f32_e32 v134, v141, v183
	v_mul_f32_e32 v134, 0x3fb8aa3b, v134
	v_exp_f32_e32 v134, v134
	v_cmp_lt_f32_e32 vcc, s51, v141
	v_add_f32_e32 v30, v138, v30
	s_nop 0
	v_cndmask_b32_e32 v141, 0, v134, vcc
	v_sub_f32_e32 v134, v142, v183
	v_mul_f32_e32 v134, 0x3fb8aa3b, v134
	v_exp_f32_e32 v134, v134
	v_cmp_lt_f32_e32 vcc, s51, v142
	v_add_f32_e32 v30, v141, v30
	s_nop 0
	v_cndmask_b32_e32 v142, 0, v134, vcc
	v_sub_f32_e32 v134, v143, v183
	v_mul_f32_e32 v134, 0x3fb8aa3b, v134
	v_exp_f32_e32 v134, v134
	v_cmp_lt_f32_e32 vcc, s51, v143
	v_add_f32_e32 v30, v142, v30
	s_nop 0
	v_cndmask_b32_e32 v185, 0, v134, vcc
	v_sub_f32_e32 v134, v136, v183
	v_cmp_lt_f32_e32 vcc, s51, v136
	v_mul_f32_e32 v134, 0x3fb8aa3b, v134
	v_sub_f32_e32 v136, v187, v183
	v_exp_f32_e32 v134, v134
	v_mul_f32_e32 v136, 0x3fb8aa3b, v136
	v_exp_f32_e32 v136, v136
	v_add_f32_e32 v30, v185, v30
	v_cndmask_b32_e32 v134, 0, v134, vcc
	v_cmp_lt_f32_e32 vcc, s51, v187
	v_add_f32_e32 v30, v134, v30
	s_nop 0
	v_cndmask_b32_e32 v139, 0, v136, vcc
	v_sub_f32_e32 v136, v188, v183
	v_mul_f32_e32 v136, 0x3fb8aa3b, v136
	v_exp_f32_e32 v136, v136
	v_cmp_lt_f32_e32 vcc, s51, v188
	v_add_f32_e32 v30, v139, v30
	s_nop 0
	v_cndmask_b32_e32 v140, 0, v136, vcc
	v_sub_f32_e32 v136, v217, v183
	v_mul_f32_e32 v136, 0x3fb8aa3b, v136
	v_exp_f32_e32 v136, v136
	v_cmp_lt_f32_e32 vcc, s51, v217
	v_add_f32_e32 v30, v140, v30
	s_nop 0
	v_cndmask_b32_e32 v143, 0, v136, vcc
	v_sub_f32_e32 v136, v218, v183
	v_mul_f32_e32 v136, 0x3fb8aa3b, v136
	v_exp_f32_e32 v136, v136
	v_cmp_lt_f32_e32 vcc, s51, v218
	v_add_f32_e32 v30, v143, v30
	s_nop 0
	v_cndmask_b32_e32 v184, 0, v136, vcc
	v_sub_f32_e32 v136, v219, v183
	v_mul_f32_e32 v136, 0x3fb8aa3b, v136
	v_exp_f32_e32 v136, v136
	v_cmp_lt_f32_e32 vcc, s51, v219
	v_add_f32_e32 v30, v184, v30
	s_nop 0
	v_cndmask_b32_e32 v186, 0, v136, vcc
	v_sub_f32_e32 v136, v220, v183
	v_mul_f32_e32 v136, 0x3fb8aa3b, v136
	v_exp_f32_e32 v136, v136
	v_cmp_lt_f32_e32 vcc, s51, v220
	v_add_f32_e32 v30, v186, v30
	s_nop 0
	v_cndmask_b32_e32 v187, 0, v136, vcc
	v_cmp_lt_f32_e32 vcc, s51, v135
	v_sub_f32_e32 v135, v135, v183
	v_mul_f32_e32 v135, 0x3fb8aa3b, v135
	v_exp_f32_e32 v135, v135
	v_add_f32_e32 v30, v187, v30
	v_cndmask_b32_e32 v188, 0, v135, vcc
	v_add_f32_e32 v135, v188, v30
	v_exp_f32_e32 v30, v221
	v_mov_b32_e32 v136, v135
	s_nop 1
	v_permlane16_swap_b32_e32 v135, v136
	v_add_f32_e32 v135, v135, v136
	v_mov_b32_e32 v136, v135
	s_nop 1
	v_permlane32_swap_b32_e32 v135, v136
	v_cmp_neq_f32_e32 vcc, 1.0, v30
	s_cbranch_vccz .LBB0_695
	v_pk_mul_f32 v[98:99], v[98:99], v[30:31] op_sel_hi:[1,0]
	v_pk_mul_f32 v[96:97], v[96:97], v[30:31] op_sel_hi:[1,0]
	v_pk_mul_f32 v[94:95], v[94:95], v[30:31] op_sel_hi:[1,0]
	v_pk_mul_f32 v[92:93], v[92:93], v[30:31] op_sel_hi:[1,0]
	v_pk_mul_f32 v[90:91], v[90:91], v[30:31] op_sel_hi:[1,0]
	v_pk_mul_f32 v[88:89], v[88:89], v[30:31] op_sel_hi:[1,0]
	v_pk_mul_f32 v[86:87], v[86:87], v[30:31] op_sel_hi:[1,0]
	v_pk_mul_f32 v[84:85], v[84:85], v[30:31] op_sel_hi:[1,0]
	v_pk_mul_f32 v[82:83], v[82:83], v[30:31] op_sel_hi:[1,0]
	v_pk_mul_f32 v[80:81], v[80:81], v[30:31] op_sel_hi:[1,0]
	v_pk_mul_f32 v[78:79], v[78:79], v[30:31] op_sel_hi:[1,0]
	v_pk_mul_f32 v[76:77], v[76:77], v[30:31] op_sel_hi:[1,0]
	v_pk_mul_f32 v[74:75], v[74:75], v[30:31] op_sel_hi:[1,0]
	v_pk_mul_f32 v[72:73], v[72:73], v[30:31] op_sel_hi:[1,0]
	v_pk_mul_f32 v[70:71], v[70:71], v[30:31] op_sel_hi:[1,0]
	v_pk_mul_f32 v[68:69], v[68:69], v[30:31] op_sel_hi:[1,0]

.LBB0_697:
	s_setprio 1
	v_cvt_pk_bf16_f32 v192, v29, v132
	v_cvt_pk_bf16_f32 v193, v133, v137
	v_cvt_pk_bf16_f32 v194, v138, v141
	v_cvt_pk_bf16_f32 v195, v142, v185
	v_cvt_pk_bf16_f32 v210, v117, v118
	v_cvt_pk_bf16_f32 v211, v119, v121
	v_cvt_pk_bf16_f32 v212, v122, v128
	v_cvt_pk_bf16_f32 v213, v129, v131
	v_add_u32_e32 v29, 0x800, v177
	v_add_u32_e32 v117, 0x1000, v177
	v_add_u32_e32 v122, 0x1800, v177
	v_add_u32_e32 v131, 0x2000, v177
	v_add_u32_e32 v132, 0x2800, v177
	v_add_u32_e32 v133, 0x3000, v177
	v_add_u32_e32 v137, 0x3800, v177
	ds_read2_b64 v[214:217], v177 offset1:4
	ds_read2_b64 v[240:243], v29 offset0:32 offset1:36
	ds_read2_b64 v[248:251], v117 offset0:64 offset1:68
	ds_read2_b64 v[252:255], v122 offset0:96 offset1:100
	s_waitcnt lgkmcnt(3)
	v_mfma_f32_16x16x32_bf16 v[96:99], v[214:217], v[192:195], v[96:99]
	v_mfma_f32_16x16x32_bf16 v[64:67], v[214:217], v[210:213], v[64:67]
	ds_read2_b64 v[214:217], v131 offset0:128 offset1:132
	s_waitcnt lgkmcnt(3)
	v_mfma_f32_16x16x32_bf16 v[92:95], v[240:243], v[192:195], v[92:95]
	v_mfma_f32_16x16x32_bf16 v[60:63], v[240:243], v[210:213], v[60:63]
	ds_read2_b64 v[240:243], v132 offset0:160 offset1:164
	s_waitcnt lgkmcnt(3)
	v_mfma_f32_16x16x32_bf16 v[88:91], v[248:251], v[192:195], v[88:91]
	v_mfma_f32_16x16x32_bf16 v[56:59], v[248:251], v[210:213], v[56:59]
	ds_read2_b64 v[248:251], v133 offset0:192 offset1:196
	s_waitcnt lgkmcnt(3)
	v_mfma_f32_16x16x32_bf16 v[84:87], v[252:255], v[192:195], v[84:87]
	v_mfma_f32_16x16x32_bf16 v[52:55], v[252:255], v[210:213], v[52:55]
	ds_read2_b64 v[252:255], v137 offset0:224 offset1:228
	s_waitcnt lgkmcnt(3)
	v_mfma_f32_16x16x32_bf16 v[80:83], v[214:217], v[192:195], v[80:83]
	v_mfma_f32_16x16x32_bf16 v[48:51], v[214:217], v[210:213], v[48:51]
	ds_read2_b64 v[214:217], v177 offset0:8 offset1:12
	s_waitcnt lgkmcnt(3)
	v_mfma_f32_16x16x32_bf16 v[76:79], v[240:243], v[192:195], v[76:79]
	v_mfma_f32_16x16x32_bf16 v[44:47], v[240:243], v[210:213], v[44:47]
	ds_read2_b64 v[240:243], v29 offset0:40 offset1:44
	s_waitcnt lgkmcnt(3)
	v_mfma_f32_16x16x32_bf16 v[72:75], v[248:251], v[192:195], v[72:75]
	v_mfma_f32_16x16x32_bf16 v[40:43], v[248:251], v[210:213], v[40:43]
	ds_read2_b64 v[248:251], v117 offset0:72 offset1:76
	s_waitcnt lgkmcnt(3)
	v_mfma_f32_16x16x32_bf16 v[68:71], v[252:255], v[192:195], v[68:71]
	v_mfma_f32_16x16x32_bf16 v[36:39], v[252:255], v[210:213], v[36:39]
	ds_read2_b64 v[252:255], v122 offset0:104 offset1:108
	v_cvt_pk_bf16_f32 v138, v134, v139
	v_cvt_pk_bf16_f32 v139, v140, v143
	v_cvt_pk_bf16_f32 v140, v184, v186
	v_cvt_pk_bf16_f32 v141, v187, v188
	v_cvt_pk_bf16_f32 v118, v120, v125
	v_cvt_pk_bf16_f32 v119, v126, v127
	v_cvt_pk_bf16_f32 v120, v130, v182
	v_cvt_pk_bf16_f32 v121, v189, v190
	s_nop 1
	s_waitcnt lgkmcnt(3)
	v_mfma_f32_16x16x32_bf16 v[96:99], v[214:217], v[138:141], v[96:99]
	v_mfma_f32_16x16x32_bf16 v[64:67], v[214:217], v[118:121], v[64:67]
	ds_read2_b64 v[214:217], v131 offset0:136 offset1:140
	s_waitcnt lgkmcnt(3)
	v_mfma_f32_16x16x32_bf16 v[92:95], v[240:243], v[138:141], v[92:95]
	v_mfma_f32_16x16x32_bf16 v[60:63], v[240:243], v[118:121], v[60:63]
	ds_read2_b64 v[240:243], v132 offset0:168 offset1:172
	s_waitcnt lgkmcnt(3)
	v_mfma_f32_16x16x32_bf16 v[88:91], v[248:251], v[138:141], v[88:91]
	v_mfma_f32_16x16x32_bf16 v[56:59], v[248:251], v[118:121], v[56:59]
	ds_read2_b64 v[248:251], v133 offset0:200 offset1:204
	s_waitcnt lgkmcnt(3)
	v_mfma_f32_16x16x32_bf16 v[84:87], v[252:255], v[138:141], v[84:87]
	v_mfma_f32_16x16x32_bf16 v[52:55], v[252:255], v[118:121], v[52:55]
	ds_read2_b64 v[252:255], v137 offset0:232 offset1:236
	s_waitcnt lgkmcnt(3)
	v_mfma_f32_16x16x32_bf16 v[80:83], v[214:217], v[138:141], v[80:83]
	v_mfma_f32_16x16x32_bf16 v[48:51], v[214:217], v[118:121], v[48:51]
	s_waitcnt lgkmcnt(2)
	v_mfma_f32_16x16x32_bf16 v[76:79], v[240:243], v[138:141], v[76:79]
	v_mfma_f32_16x16x32_bf16 v[44:47], v[240:243], v[118:121], v[44:47]
	s_waitcnt lgkmcnt(1)
	v_mfma_f32_16x16x32_bf16 v[72:75], v[248:251], v[138:141], v[72:75]
	v_mfma_f32_16x16x32_bf16 v[40:43], v[248:251], v[118:121], v[40:43]
	s_waitcnt lgkmcnt(0)
	v_mfma_f32_16x16x32_bf16 v[68:71], v[252:255], v[138:141], v[68:71]
	v_mfma_f32_16x16x32_bf16 v[36:39], v[252:255], v[118:121], v[36:39]
	s_setprio 0
	s_andn2_b64 vcc, exec, s[14:15]
	s_cbranch_vccnz .LBB0_699
	v_add_u32_e32 v29, v174, v157
	s_waitcnt vmcnt(3)
	ds_write_b128 v29, v[104:107] offset:11328
	v_add_u32_e32 v29, v174, v168
	s_waitcnt vmcnt(2)
	ds_write_b128 v29, v[108:111] offset:11328
	v_add_u32_e32 v29, v173, v154
	s_waitcnt vmcnt(1)
	ds_write_b128 v29, v[112:115] offset:28736
	v_add_u32_e32 v29, v173, v171
	s_waitcnt vmcnt(0)
	ds_write_b128 v29, v[100:103] offset:28736

.LBB0_704:
	s_setprio 1
	ds_read_b128 v[186:189], v178 offset:11328
	ds_read_b128 v[240:243], v178 offset:11392
	ds_read_b128 v[248:251], v178 offset:11456
	ds_read_b128 v[252:255], v178 offset:11520
	s_waitcnt lgkmcnt(3)
	v_mfma_f32_16x16x32_bf16 v[190:193], v[186:189], v[0:3], 0
	v_mfma_f32_16x16x32_bf16 v[128:131], v[186:189], v[16:19], 0
	ds_read_b128 v[186:189], v178 offset:15680
	s_waitcnt lgkmcnt(3)
	v_mfma_f32_16x16x32_bf16 v[190:193], v[240:243], v[4:7], v[190:193]
	v_mfma_f32_16x16x32_bf16 v[128:131], v[240:243], v[20:23], v[128:131]
	ds_read_b128 v[240:243], v178 offset:15744
	s_waitcnt lgkmcnt(3)
	v_mfma_f32_16x16x32_bf16 v[190:193], v[248:251], v[8:11], v[190:193]
	v_mfma_f32_16x16x32_bf16 v[128:131], v[248:251], v[24:27], v[128:131]
	ds_read_b128 v[248:251], v178 offset:15808
	s_waitcnt lgkmcnt(3)
	v_mfma_f32_16x16x32_bf16 v[190:193], v[252:255], v[12:15], v[190:193]
	v_mfma_f32_16x16x32_bf16 v[128:131], v[252:255], v[32:35], v[128:131]
	ds_read_b128 v[252:255], v178 offset:15872
	s_waitcnt lgkmcnt(3)
	v_mfma_f32_16x16x32_bf16 v[140:143], v[186:189], v[0:3], 0
	v_mfma_f32_16x16x32_bf16 v[124:127], v[186:189], v[16:19], 0
	ds_read_b128 v[186:189], v178 offset:20032
	s_waitcnt lgkmcnt(3)
	v_mfma_f32_16x16x32_bf16 v[140:143], v[240:243], v[4:7], v[140:143]
	v_mfma_f32_16x16x32_bf16 v[124:127], v[240:243], v[20:23], v[124:127]
	ds_read_b128 v[240:243], v178 offset:20096
	s_waitcnt lgkmcnt(3)
	v_mfma_f32_16x16x32_bf16 v[140:143], v[248:251], v[8:11], v[140:143]
	v_mfma_f32_16x16x32_bf16 v[124:127], v[248:251], v[24:27], v[124:127]
	ds_read_b128 v[248:251], v178 offset:20160
	s_waitcnt lgkmcnt(3)
	v_mfma_f32_16x16x32_bf16 v[140:143], v[252:255], v[12:15], v[140:143]
	v_mfma_f32_16x16x32_bf16 v[124:127], v[252:255], v[32:35], v[124:127]
	ds_read_b128 v[252:255], v178 offset:20224
	s_waitcnt lgkmcnt(3)
	v_mfma_f32_16x16x32_bf16 v[136:139], v[186:189], v[0:3], 0
	v_mfma_f32_16x16x32_bf16 v[120:123], v[186:189], v[16:19], 0
	ds_read_b128 v[186:189], v178 offset:24384
	s_waitcnt lgkmcnt(3)
	v_mfma_f32_16x16x32_bf16 v[136:139], v[240:243], v[4:7], v[136:139]
	v_mfma_f32_16x16x32_bf16 v[120:123], v[240:243], v[20:23], v[120:123]
	ds_read_b128 v[240:243], v178 offset:24448
	s_waitcnt lgkmcnt(3)
	v_mfma_f32_16x16x32_bf16 v[136:139], v[248:251], v[8:11], v[136:139]
	v_mfma_f32_16x16x32_bf16 v[120:123], v[248:251], v[24:27], v[120:123]
	ds_read_b128 v[248:251], v178 offset:24512
	s_waitcnt lgkmcnt(3)
	v_mfma_f32_16x16x32_bf16 v[136:139], v[252:255], v[12:15], v[136:139]
	v_mfma_f32_16x16x32_bf16 v[120:123], v[252:255], v[32:35], v[120:123]
	ds_read_b128 v[252:255], v178 offset:24576
	s_waitcnt lgkmcnt(3)
	v_mfma_f32_16x16x32_bf16 v[132:135], v[186:189], v[0:3], 0
	v_mfma_f32_16x16x32_bf16 v[116:119], v[186:189], v[16:19], 0
	s_waitcnt lgkmcnt(2)
	v_mfma_f32_16x16x32_bf16 v[132:135], v[240:243], v[4:7], v[132:135]
	v_mfma_f32_16x16x32_bf16 v[116:119], v[240:243], v[20:23], v[116:119]
	s_waitcnt lgkmcnt(1)
	v_mfma_f32_16x16x32_bf16 v[132:135], v[248:251], v[8:11], v[132:135]
	v_mfma_f32_16x16x32_bf16 v[116:119], v[248:251], v[24:27], v[116:119]
	s_waitcnt lgkmcnt(0)
	v_mfma_f32_16x16x32_bf16 v[132:135], v[252:255], v[12:15], v[132:135]
	v_mfma_f32_16x16x32_bf16 v[116:119], v[252:255], v[32:35], v[116:119]
	s_setprio 0
	v_lshl_add_u32 v189, s2, 6, v155
	v_sub_u32_e32 v29, v160, v189
	v_cmp_gt_u32_e64 s[8:9], s75, v29
	v_med3_i32 v29, v29, 0, v207
	v_lshl_add_u32 v29, v29, 2, v151
	ds_read_b32 v182, v29 offset:9216
	v_sub_u32_e32 v187, v175, v189
	v_add_u32_e32 v213, 17, v189
	v_add_u32_e32 v214, 18, v189
	v_add_u32_e32 v215, 19, v189
	s_waitcnt lgkmcnt(0)
	v_add_f32_e32 v29, v190, v182
	v_or_b32_e32 v190, 1, v189
	v_cndmask_b32_e64 v30, v208, v29, s[8:9]
	v_sub_u32_e32 v29, v160, v190
	v_cmp_gt_u32_e32 vcc, s75, v29
	v_med3_i32 v29, v29, 0, v207
	v_lshl_add_u32 v29, v29, 2, v151
	ds_read_b32 v29, v29 offset:9216
	v_add_u32_e32 v216, 32, v189
	v_add_u32_e32 v194, 34, v189
	v_add_u32_e32 v195, 35, v189
	v_add_u32_e32 v209, 48, v189
	s_waitcnt lgkmcnt(0)
	v_add_f32_e32 v29, v191, v29
	v_or_b32_e32 v191, 2, v189
	v_sub_u32_e32 v181, v160, v191
	v_cndmask_b32_e32 v180, v208, v29, vcc
	v_cmp_gt_u32_e32 vcc, s75, v181
	v_med3_i32 v181, v181, 0, v207
	v_lshl_add_u32 v181, v181, 2, v151
	ds_read_b32 v181, v181 offset:9216
	v_add_u32_e32 v210, 49, v189
	v_add_u32_e32 v211, 50, v189
	v_add_u32_e32 v212, 51, v189
	v_max3_f32 v29, v30, s82, v180
	s_waitcnt lgkmcnt(0)
	v_add_f32_e32 v181, v192, v181
	v_or_b32_e32 v192, 3, v189
	v_sub_u32_e32 v186, v160, v192
	v_cndmask_b32_e32 v181, v208, v181, vcc
	v_cmp_gt_u32_e32 vcc, s75, v186
	v_med3_i32 v186, v186, 0, v207
	v_lshl_add_u32 v186, v186, 2, v151
	ds_read_b32 v186, v186 offset:9216
	s_waitcnt lgkmcnt(0)
	v_add_f32_e32 v186, v193, v186
	v_cndmask_b32_e32 v186, v208, v186, vcc
	v_cmp_gt_u32_e32 vcc, s75, v187
	v_med3_i32 v187, v187, 0, v207
	v_lshl_add_u32 v187, v187, 2, v151
	ds_read_b32 v187, v187 offset:9216
	v_add_u32_e32 v193, 33, v189
	v_max3_f32 v29, v29, v181, v186
	s_waitcnt lgkmcnt(0)
	v_add_f32_e32 v140, v140, v187
	v_sub_u32_e32 v187, v160, v213
	v_cndmask_b32_e32 v140, v208, v140, vcc
	v_cmp_gt_u32_e32 vcc, s75, v187
	v_med3_i32 v187, v187, 0, v207
	v_lshl_add_u32 v187, v187, 2, v151
	ds_read_b32 v187, v187 offset:9216
	s_waitcnt lgkmcnt(0)
	v_add_f32_e32 v141, v141, v187
	v_sub_u32_e32 v187, v160, v214
	v_cndmask_b32_e32 v141, v208, v141, vcc
	v_cmp_gt_u32_e32 vcc, s75, v187
	v_med3_i32 v187, v187, 0, v207
	v_lshl_add_u32 v187, v187, 2, v151
	ds_read_b32 v187, v187 offset:9216
	v_max3_f32 v29, v29, v140, v141
	s_waitcnt lgkmcnt(0)
	v_add_f32_e32 v142, v142, v187
	v_cndmask_b32_e32 v187, v208, v142, vcc
	v_sub_u32_e32 v142, v160, v215
	v_cmp_gt_u32_e32 vcc, s75, v142
	v_med3_i32 v142, v142, 0, v207
	v_lshl_add_u32 v142, v142, 2, v151
	ds_read_b32 v142, v142 offset:9216
	s_waitcnt lgkmcnt(0)
	v_add_f32_e32 v142, v143, v142
	v_cndmask_b32_e32 v188, v208, v142, vcc
	v_sub_u32_e32 v142, v160, v216
	v_cmp_gt_u32_e32 vcc, s75, v142
	v_med3_i32 v142, v142, 0, v207
	v_lshl_add_u32 v142, v142, 2, v151
	ds_read_b32 v142, v142 offset:9216
	v_max3_f32 v29, v29, v187, v188
	s_waitcnt lgkmcnt(0)
	v_add_f32_e32 v136, v136, v142
	v_cndmask_b32_e32 v217, v208, v136, vcc
	v_sub_u32_e32 v136, v160, v193
	v_cmp_gt_u32_e32 vcc, s75, v136
	v_med3_i32 v136, v136, 0, v207
	v_lshl_add_u32 v136, v136, 2, v151
	ds_read_b32 v136, v136 offset:9216
	s_waitcnt lgkmcnt(0)
	v_add_f32_e32 v136, v137, v136
	v_cndmask_b32_e32 v218, v208, v136, vcc
	v_sub_u32_e32 v136, v160, v194
	v_cmp_gt_u32_e32 vcc, s75, v136
	v_med3_i32 v136, v136, 0, v207
	v_lshl_add_u32 v136, v136, 2, v151
	ds_read_b32 v136, v136 offset:9216
	v_max3_f32 v29, v29, v217, v218
	s_waitcnt lgkmcnt(0)
	v_add_f32_e32 v136, v138, v136
	v_cndmask_b32_e32 v138, v208, v136, vcc
	v_sub_u32_e32 v136, v160, v195
	v_cmp_gt_u32_e32 vcc, s75, v136
	v_med3_i32 v136, v136, 0, v207
	v_lshl_add_u32 v136, v136, 2, v151
	ds_read_b32 v136, v136 offset:9216
	s_waitcnt lgkmcnt(0)
	v_add_f32_e32 v136, v139, v136
	v_cndmask_b32_e32 v219, v208, v136, vcc
	v_sub_u32_e32 v136, v160, v209
	v_cmp_gt_u32_e32 vcc, s75, v136
	v_med3_i32 v136, v136, 0, v207
	v_lshl_add_u32 v136, v136, 2, v151
	ds_read_b32 v136, v136 offset:9216
	v_max3_f32 v29, v29, v138, v219
	s_waitcnt lgkmcnt(0)
	v_add_f32_e32 v132, v132, v136
	v_cndmask_b32_e32 v220, v208, v132, vcc
	v_sub_u32_e32 v132, v160, v210
	v_cmp_gt_u32_e32 vcc, s75, v132
	v_med3_i32 v132, v132, 0, v207
	v_lshl_add_u32 v132, v132, 2, v151
	ds_read_b32 v132, v132 offset:9216
	s_waitcnt lgkmcnt(0)
	v_add_f32_e32 v132, v133, v132
	v_cndmask_b32_e32 v221, v208, v132, vcc
	v_sub_u32_e32 v132, v160, v211
	v_cmp_gt_u32_e32 vcc, s75, v132
	v_med3_i32 v132, v132, 0, v207
	v_lshl_add_u32 v132, v132, 2, v151
	ds_read_b32 v132, v132 offset:9216
	v_max3_f32 v29, v29, v220, v221
	s_waitcnt lgkmcnt(0)
	v_add_f32_e32 v132, v134, v132
	v_cndmask_b32_e32 v222, v208, v132, vcc
	v_sub_u32_e32 v132, v160, v212
	v_cmp_gt_u32_e32 vcc, s75, v132
	v_med3_i32 v132, v132, 0, v207
	v_lshl_add_u32 v132, v132, 2, v151
	ds_read_b32 v132, v132 offset:9216
	s_waitcnt lgkmcnt(0)
	v_add_f32_e32 v132, v135, v132
	v_cndmask_b32_e32 v223, v208, v132, vcc
	v_max3_f32 v29, v29, v222, v223
	v_mov_b32_e32 v132, v29
	s_nop 1
	v_permlane16_swap_b32_e32 v29, v132
	v_max_f32_e32 v132, v132, v132
	v_max_f32_e32 v29, v29, v29
	v_max_f32_e32 v29, v29, v132
	v_mov_b32_e32 v132, v29
	s_nop 1
	v_permlane32_swap_b32_e32 v29, v132
	v_max3_f32 v29, v183, v29, v132
	v_cmp_lt_f32_e32 vcc, s51, v30
	v_sub_f32_e32 v30, v30, v29
	v_mul_f32_e32 v30, 0x3fb8aa3b, v30
	v_sub_f32_e32 v133, v180, v29
	v_exp_f32_e32 v30, v30
	v_mul_f32_e32 v133, 0x3fb8aa3b, v133
	v_sub_f32_e32 v134, v181, v29
	v_exp_f32_e32 v133, v133
	v_mul_f32_e32 v134, 0x3fb8aa3b, v134
	v_sub_f32_e32 v135, v186, v29
	v_exp_f32_e32 v134, v134
	v_mul_f32_e32 v135, 0x3fb8aa3b, v135
	v_sub_f32_e32 v132, v183, v29
	v_exp_f32_e32 v135, v135
	v_mul_f32_e32 v224, 0x3fb8aa3b, v132
	v_cndmask_b32_e32 v132, 0, v30, vcc
	v_cmp_lt_f32_e32 vcc, s51, v180
	v_sub_f32_e32 v139, v218, v29
	v_mul_f32_e32 v139, 0x3fb8aa3b, v139
	v_cndmask_b32_e32 v133, 0, v133, vcc
	v_cmp_lt_f32_e32 vcc, s51, v181
	v_exp_f32_e32 v139, v139
	v_add_f32_e32 v30, 0, v132
	v_cndmask_b32_e32 v134, 0, v134, vcc
	v_cmp_lt_f32_e32 vcc, s51, v186
	v_add_f32_e32 v30, v133, v30
	v_add_f32_e32 v30, v134, v30
	v_cndmask_b32_e32 v136, 0, v135, vcc
	v_sub_f32_e32 v135, v140, v29
	v_mul_f32_e32 v135, 0x3fb8aa3b, v135
	v_exp_f32_e32 v135, v135
	v_cmp_lt_f32_e32 vcc, s51, v140
	v_add_f32_e32 v30, v136, v30
	s_nop 0
	v_cndmask_b32_e32 v137, 0, v135, vcc
	v_sub_f32_e32 v135, v141, v29
	v_mul_f32_e32 v135, 0x3fb8aa3b, v135
	v_exp_f32_e32 v135, v135
	v_cmp_lt_f32_e32 vcc, s51, v141
	v_add_f32_e32 v30, v137, v30
	s_nop 0
	v_cndmask_b32_e32 v142, 0, v135, vcc
	v_sub_f32_e32 v135, v187, v29
	v_mul_f32_e32 v135, 0x3fb8aa3b, v135
	v_exp_f32_e32 v135, v135
	v_cmp_lt_f32_e32 vcc, s51, v187
	v_add_f32_e32 v30, v142, v30
	s_nop 0
	v_cndmask_b32_e32 v143, 0, v135, vcc
	v_sub_f32_e32 v135, v188, v29
	v_mul_f32_e32 v135, 0x3fb8aa3b, v135
	v_exp_f32_e32 v135, v135
	v_cmp_lt_f32_e32 vcc, s51, v188
	v_add_f32_e32 v30, v143, v30
	s_nop 0
	v_cndmask_b32_e32 v183, 0, v135, vcc
	v_sub_f32_e32 v135, v217, v29
	v_mul_f32_e32 v135, 0x3fb8aa3b, v135
	v_exp_f32_e32 v135, v135
	v_cmp_lt_f32_e32 vcc, s51, v217
	v_add_f32_e32 v30, v183, v30
	s_nop 0
	v_cndmask_b32_e32 v135, 0, v135, vcc
	v_cmp_lt_f32_e32 vcc, s51, v218
	v_add_f32_e32 v30, v135, v30
	s_nop 0
	v_cndmask_b32_e32 v139, 0, v139, vcc
	v_cmp_lt_f32_e32 vcc, s51, v138
	v_sub_f32_e32 v138, v138, v29
	v_mul_f32_e32 v138, 0x3fb8aa3b, v138
	v_exp_f32_e32 v138, v138
	v_add_f32_e32 v30, v139, v30
	v_cndmask_b32_e32 v141, 0, v138, vcc
	v_sub_f32_e32 v138, v219, v29
	v_mul_f32_e32 v138, 0x3fb8aa3b, v138
	v_exp_f32_e32 v138, v138
	v_cmp_lt_f32_e32 vcc, s51, v219
	v_add_f32_e32 v30, v141, v30
	s_nop 0
	v_cndmask_b32_e32 v180, 0, v138, vcc
	v_sub_f32_e32 v138, v220, v29
	v_mul_f32_e32 v138, 0x3fb8aa3b, v138
	v_exp_f32_e32 v138, v138
	v_cmp_lt_f32_e32 vcc, s51, v220
	v_add_f32_e32 v30, v180, v30
	s_nop 0
	v_cndmask_b32_e32 v181, 0, v138, vcc
	v_sub_f32_e32 v138, v221, v29
	v_mul_f32_e32 v138, 0x3fb8aa3b, v138
	v_exp_f32_e32 v138, v138
	v_cmp_lt_f32_e32 vcc, s51, v221
	v_add_f32_e32 v30, v181, v30
	s_nop 0
	v_cndmask_b32_e32 v186, 0, v138, vcc
	v_sub_f32_e32 v138, v222, v29
	v_mul_f32_e32 v138, 0x3fb8aa3b, v138
	v_exp_f32_e32 v138, v138
	v_cmp_lt_f32_e32 vcc, s51, v222
	v_add_f32_e32 v30, v186, v30
	s_nop 0
	v_cndmask_b32_e32 v187, 0, v138, vcc
	v_sub_f32_e32 v138, v223, v29
	v_mul_f32_e32 v138, 0x3fb8aa3b, v138
	v_exp_f32_e32 v138, v138
	v_cmp_lt_f32_e32 vcc, s51, v223
	v_add_f32_e32 v30, v187, v30
	s_nop 0
	v_cndmask_b32_e32 v188, 0, v138, vcc
	v_add_f32_e32 v138, v188, v30
	v_exp_f32_e32 v30, v224
	v_mov_b32_e32 v140, v138
	s_nop 1
	v_permlane16_swap_b32_e32 v138, v140
	v_add_f32_e32 v138, v138, v140
	v_mov_b32_e32 v140, v138
	s_nop 1
	v_permlane32_swap_b32_e32 v138, v140
	v_cmp_neq_f32_e32 vcc, 1.0, v30
	s_cbranch_vccz .LBB0_706
	v_pk_mul_f32 v[98:99], v[98:99], v[30:31] op_sel_hi:[1,0]
	v_pk_mul_f32 v[96:97], v[96:97], v[30:31] op_sel_hi:[1,0]
	v_pk_mul_f32 v[94:95], v[94:95], v[30:31] op_sel_hi:[1,0]
	v_pk_mul_f32 v[92:93], v[92:93], v[30:31] op_sel_hi:[1,0]
	v_pk_mul_f32 v[90:91], v[90:91], v[30:31] op_sel_hi:[1,0]
	v_pk_mul_f32 v[88:89], v[88:89], v[30:31] op_sel_hi:[1,0]
	v_pk_mul_f32 v[86:87], v[86:87], v[30:31] op_sel_hi:[1,0]
	v_pk_mul_f32 v[84:85], v[84:85], v[30:31] op_sel_hi:[1,0]
	v_pk_mul_f32 v[82:83], v[82:83], v[30:31] op_sel_hi:[1,0]
	v_pk_mul_f32 v[80:81], v[80:81], v[30:31] op_sel_hi:[1,0]
	v_pk_mul_f32 v[78:79], v[78:79], v[30:31] op_sel_hi:[1,0]
	v_pk_mul_f32 v[76:77], v[76:77], v[30:31] op_sel_hi:[1,0]
	v_pk_mul_f32 v[74:75], v[74:75], v[30:31] op_sel_hi:[1,0]
	v_pk_mul_f32 v[72:73], v[72:73], v[30:31] op_sel_hi:[1,0]
	v_pk_mul_f32 v[70:71], v[70:71], v[30:31] op_sel_hi:[1,0]
	v_pk_mul_f32 v[68:69], v[68:69], v[30:31] op_sel_hi:[1,0]

.LBB0_708:
	s_setprio 1
	v_cvt_pk_bf16_f32 v192, v132, v133
	v_cvt_pk_bf16_f32 v193, v134, v136
	v_cvt_pk_bf16_f32 v194, v137, v142
	v_cvt_pk_bf16_f32 v195, v143, v183
	v_cvt_pk_bf16_f32 v210, v31, v117
	v_cvt_pk_bf16_f32 v211, v118, v120
	v_cvt_pk_bf16_f32 v212, v121, v128
	v_cvt_pk_bf16_f32 v213, v126, v130
	v_add_u32_e32 v31, 0x7000, v179
	v_add_u32_e32 v117, 0x7800, v179
	v_add_u32_e32 v130, 0x8000, v179
	v_add_u32_e32 v136, 0x8800, v179
	v_add_u32_e32 v137, 0x9000, v179
	v_add_u32_e32 v142, 0x9800, v179
	v_add_u32_e32 v143, 0xa000, v179
	v_add_u32_e32 v183, 0xa800, v179
	ds_read2_b64 v[214:217], v31 offset0:8 offset1:12
	ds_read2_b64 v[240:243], v117 offset0:40 offset1:44
	ds_read2_b64 v[248:251], v130 offset0:72 offset1:76
	ds_read2_b64 v[252:255], v136 offset0:104 offset1:108
	s_waitcnt lgkmcnt(3)
	v_mfma_f32_16x16x32_bf16 v[96:99], v[214:217], v[192:195], v[96:99]
	v_mfma_f32_16x16x32_bf16 v[64:67], v[214:217], v[210:213], v[64:67]
	ds_read2_b64 v[214:217], v137 offset0:136 offset1:140
	s_waitcnt lgkmcnt(3)
	v_mfma_f32_16x16x32_bf16 v[92:95], v[240:243], v[192:195], v[92:95]
	v_mfma_f32_16x16x32_bf16 v[60:63], v[240:243], v[210:213], v[60:63]
	ds_read2_b64 v[240:243], v142 offset0:168 offset1:172
	s_waitcnt lgkmcnt(3)
	v_mfma_f32_16x16x32_bf16 v[88:91], v[248:251], v[192:195], v[88:91]
	v_mfma_f32_16x16x32_bf16 v[56:59], v[248:251], v[210:213], v[56:59]
	ds_read2_b64 v[248:251], v143 offset0:200 offset1:204
	s_waitcnt lgkmcnt(3)
	v_mfma_f32_16x16x32_bf16 v[84:87], v[252:255], v[192:195], v[84:87]
	v_mfma_f32_16x16x32_bf16 v[52:55], v[252:255], v[210:213], v[52:55]
	ds_read2_b64 v[252:255], v183 offset0:232 offset1:236
	s_waitcnt lgkmcnt(3)
	v_mfma_f32_16x16x32_bf16 v[80:83], v[214:217], v[192:195], v[80:83]
	v_mfma_f32_16x16x32_bf16 v[48:51], v[214:217], v[210:213], v[48:51]
	ds_read2_b64 v[214:217], v31 offset0:16 offset1:20
	s_waitcnt lgkmcnt(3)
	v_mfma_f32_16x16x32_bf16 v[76:79], v[240:243], v[192:195], v[76:79]
	v_mfma_f32_16x16x32_bf16 v[44:47], v[240:243], v[210:213], v[44:47]
	ds_read2_b64 v[240:243], v117 offset0:48 offset1:52
	s_waitcnt lgkmcnt(3)
	v_mfma_f32_16x16x32_bf16 v[72:75], v[248:251], v[192:195], v[72:75]
	v_mfma_f32_16x16x32_bf16 v[40:43], v[248:251], v[210:213], v[40:43]
	ds_read2_b64 v[248:251], v130 offset0:80 offset1:84
	s_waitcnt lgkmcnt(3)
	v_mfma_f32_16x16x32_bf16 v[68:71], v[252:255], v[192:195], v[68:71]
	v_mfma_f32_16x16x32_bf16 v[36:39], v[252:255], v[210:213], v[36:39]
	ds_read2_b64 v[252:255], v136 offset0:112 offset1:116
	v_cvt_pk_bf16_f32 v132, v135, v139
	v_cvt_pk_bf16_f32 v133, v141, v180
	v_cvt_pk_bf16_f32 v134, v181, v186
	v_cvt_pk_bf16_f32 v135, v187, v188
	v_cvt_pk_bf16_f32 v118, v119, v122
	v_cvt_pk_bf16_f32 v119, v123, v127
	v_cvt_pk_bf16_f32 v120, v129, v131
	v_cvt_pk_bf16_f32 v121, v189, v190
	s_nop 1
	s_waitcnt lgkmcnt(3)
	v_mfma_f32_16x16x32_bf16 v[96:99], v[214:217], v[132:135], v[96:99]
	v_mfma_f32_16x16x32_bf16 v[64:67], v[214:217], v[118:121], v[64:67]
	ds_read2_b64 v[214:217], v137 offset0:144 offset1:148
	s_waitcnt lgkmcnt(3)
	v_mfma_f32_16x16x32_bf16 v[92:95], v[240:243], v[132:135], v[92:95]
	v_mfma_f32_16x16x32_bf16 v[60:63], v[240:243], v[118:121], v[60:63]
	ds_read2_b64 v[240:243], v142 offset0:176 offset1:180
	s_waitcnt lgkmcnt(3)
	v_mfma_f32_16x16x32_bf16 v[88:91], v[248:251], v[132:135], v[88:91]
	v_mfma_f32_16x16x32_bf16 v[56:59], v[248:251], v[118:121], v[56:59]
	ds_read2_b64 v[248:251], v143 offset0:208 offset1:212
	s_waitcnt lgkmcnt(3)
	v_mfma_f32_16x16x32_bf16 v[84:87], v[252:255], v[132:135], v[84:87]
	v_mfma_f32_16x16x32_bf16 v[52:55], v[252:255], v[118:121], v[52:55]
	ds_read2_b64 v[252:255], v183 offset0:240 offset1:244
	s_waitcnt lgkmcnt(3)
	v_mfma_f32_16x16x32_bf16 v[80:83], v[214:217], v[132:135], v[80:83]
	v_mfma_f32_16x16x32_bf16 v[48:51], v[214:217], v[118:121], v[48:51]
	s_waitcnt lgkmcnt(2)
	v_mfma_f32_16x16x32_bf16 v[76:79], v[240:243], v[132:135], v[76:79]
	v_mfma_f32_16x16x32_bf16 v[44:47], v[240:243], v[118:121], v[44:47]
	s_waitcnt lgkmcnt(1)
	v_mfma_f32_16x16x32_bf16 v[72:75], v[248:251], v[132:135], v[72:75]
	v_mfma_f32_16x16x32_bf16 v[40:43], v[248:251], v[118:121], v[40:43]
	s_waitcnt lgkmcnt(0)
	v_mfma_f32_16x16x32_bf16 v[68:71], v[252:255], v[132:135], v[68:71]
	v_mfma_f32_16x16x32_bf16 v[36:39], v[252:255], v[118:121], v[36:39]
	s_setprio 0
	s_andn2_b64 vcc, exec, s[12:13]
	s_cbranch_vccnz .LBB0_690
	s_waitcnt vmcnt(3)
	ds_write_b128 v161, v[104:107]
	s_waitcnt vmcnt(2)
	ds_write_b128 v169, v[108:111]
	s_waitcnt vmcnt(1)
	ds_write_b128 v170, v[112:115]
	s_waitcnt vmcnt(0)
	ds_write_b128 v172, v[100:103]
	s_branch .LBB0_690

	.amdhsa_kernel _Z4mega6Params
		.amdhsa_group_segment_fixed_size 10240
		.amdhsa_private_segment_fixed_size 0
		.amdhsa_kernarg_size 568
		.amdhsa_user_sgpr_count 2
		.amdhsa_user_sgpr_dispatch_ptr 0
		.amdhsa_user_sgpr_queue_ptr 0
		.amdhsa_user_sgpr_kernarg_segment_ptr 1
		.amdhsa_user_sgpr_dispatch_id 0
		.amdhsa_user_sgpr_kernarg_preload_length 0
		.amdhsa_user_sgpr_kernarg_preload_offset 0
		.amdhsa_user_sgpr_private_segment_size 0
		.amdhsa_uses_dynamic_stack 0
		.amdhsa_enable_private_segment 0
		.amdhsa_system_sgpr_workgroup_id_x 1
		.amdhsa_system_sgpr_workgroup_id_y 0
		.amdhsa_system_sgpr_workgroup_id_z 0
		.amdhsa_system_sgpr_workgroup_info 0
		.amdhsa_system_vgpr_workitem_id 2
		.amdhsa_next_free_vgpr 256
		.amdhsa_next_free_sgpr 100
		.amdhsa_accum_offset 256
		.amdhsa_reserve_vcc 1
		.amdhsa_float_round_mode_32 0
		.amdhsa_float_round_mode_16_64 0
		.amdhsa_float_denorm_mode_32 3
		.amdhsa_float_denorm_mode_16_64 3
		.amdhsa_dx10_clamp 1
		.amdhsa_ieee_mode 1
		.amdhsa_fp16_overflow 0
		.amdhsa_tg_split 0
		.amdhsa_exception_fp_ieee_invalid_op 0
		.amdhsa_exception_fp_denorm_src 0
		.amdhsa_exception_fp_ieee_div_zero 0
		.amdhsa_exception_fp_ieee_overflow 0
		.amdhsa_exception_fp_ieee_underflow 0
		.amdhsa_exception_fp_ieee_inexact 0
		.amdhsa_exception_int_div_zero 0
	.end_amdhsa_kernel

amdhsa.kernels:
  - .agpr_count:     0
    .args:
      - .offset:         0
        .size:           312
        .value_kind:     by_value
      - .offset:         312
        .size:           4
        .value_kind:     hidden_block_count_x
      - .offset:         316
        .size:           4
        .value_kind:     hidden_block_count_y
      - .offset:         320
        .size:           4
        .value_kind:     hidden_block_count_z
      - .offset:         324
        .size:           2
        .value_kind:     hidden_group_size_x
      - .offset:         326
        .size:           2
        .value_kind:     hidden_group_size_y
      - .offset:         328
        .size:           2
        .value_kind:     hidden_group_size_z
      - .offset:         330
        .size:           2
        .value_kind:     hidden_remainder_x
      - .offset:         332
        .size:           2
        .value_kind:     hidden_remainder_y
      - .offset:         334
        .size:           2
        .value_kind:     hidden_remainder_z
      - .offset:         352
        .size:           8
        .value_kind:     hidden_global_offset_x
      - .offset:         360
        .size:           8
        .value_kind:     hidden_global_offset_y
      - .offset:         368
        .size:           8
        .value_kind:     hidden_global_offset_z
      - .offset:         376
        .size:           2
        .value_kind:     hidden_grid_dims
      - .offset:         400
        .size:           8
        .value_kind:     hidden_multigrid_sync_arg
      - .offset:         432
        .size:           4
        .value_kind:     hidden_dynamic_lds_size
    .group_segment_fixed_size: 10240
    .kernarg_segment_align: 8
    .kernarg_segment_size: 568
    .language:       OpenCL C
    .language_version:
      - 2
      - 0
    .max_flat_workgroup_size: 512
    .name:           _Z4mega6Params
    .private_segment_fixed_size: 0
    .sgpr_count:     106
    .sgpr_spill_count: 189
    .symbol:         _Z4mega6Params.kd
    .uniform_work_group_size: 1
    .uses_dynamic_stack: false
    .vgpr_count:     256
    .vgpr_spill_count: 0
    .wavefront_size: 64
